# LDS-DMA tile loads issued in the QK segment's gaps 16-21 (no fragment reads there) instead of gaps 0-12
# speedup vs baseline: 1.0052x; 1.0042x over previous
; __device__ __forceinline__ void partialSM(f32x16& p0, f32x16& p1, float& m_reg, float& mn, float& alpha) {
;     ...
;   for (int r = 0; r < 16; ++r) p0[r] = __builtin_amdgcn_exp2f(p0[r]);
; }
; __device__ __forceinline__ void finishSM(f32x16& p0, f32x16& p1, float alpha, float& l_reg, bf16x8& pa0, bf16x8& pa1, bf16x8& pa2, bf16x8& pa3) {
; #pragma unroll
;   for (int r = 0; r < 16; ++r) p1[r] = __builtin_amdgcn_exp2f(p1[r]);
;   float ps = 0;
; #pragma unroll
;   for (int r = 0; r < 16; ++r) ps += p0[r];
; #pragma unroll
;   for (int r = 0; r < 16; ++r) ps += p1[r];
;   { auto rr = __builtin_amdgcn_permlane32_swap(__float_as_uint(ps), __float_as_uint(ps), false, false);
;     ps = __uint_as_float(rr[0]) + __uint_as_float(rr[1]); }
;   l_reg = l_reg * alpha + ps;
;     ...
;   PK4(p0, 0, pa0); PK4(p0, 8, pa1); PK4(p1, 0, pa2); PK4(p1, 8, pa3);
;     ...
; }
; __device__ __forceinline__ void qkt(f32x16& p0, f32x16& p1, const bf16* Ks, const bf16x8* qr, int r32, int hi) {
;   p0 = f32x16{}; p1 = f32x16{};
; #pragma unroll
;   for (int d0 = 0; d0 < 8; ++d0) { int cb = (d0 * 16 + hi * 8) * 2;
;     bf16x8 b0 = *reinterpret_cast<const bf16x8*>((const char*)Ks + KSWZ(r32, cb));
;     bf16x8 b1 = *reinterpret_cast<const bf16x8*>((const char*)Ks + KSWZ(32 + r32, cb));
;     p0 = __builtin_amdgcn_mfma_f32_32x32x16_bf16(b0, qr[d0], p0, 0, 0, 0);
;     p1 = __builtin_amdgcn_mfma_f32_32x32x16_bf16(b1, qr[d0], p1, 0, 0, 0); }
; }
; __device__ __forceinline__ int v_st(int k, int c) { const int kk = (k & ~0xC) | ((k & 4) << 1) | ((k & 8) >> 1); return ((kk >> 3) * 4 + (c >> 5)) * 512 + ((kk & 7) * 32 + (c & 31)) * 2; }
; __device__ __forceinline__ int v_rd_base(int lane) { return ((lane & 3) << 3) | (((lane >> 2) & 3) << 6) | (((lane >> 4) & 1) << 5) | (((lane >> 5) & 1) << 8); }
; template <int OFF> __device__ __forceinline__ s16x4 tr_read(int vb) {
;   s16x4 r; asm volatile("ds_read_b64_tr_b16 %0, %1 offset:%2" : "=&v"(r) : "v"(vb), "i"(OFF) : "memory"); return r;
; }
; template <int D0> __device__ __forceinline__ void pv_one(f32x16& od, int vb, bf16x8 pa0, bf16x8 pa1, bf16x8 pa2, bf16x8 pa3) {
;   const s16x4 l0 = tr_read<v_rd_off(D0, 0, 0)>(vb), h0 = tr_read<v_rd_off(D0, 0, 1)>(vb), l1 = tr_read<v_rd_off(D0, 1, 0)>(vb), h1 = tr_read<v_rd_off(D0, 1, 1)>(vb);
.Lprio_done:
.Ldense_loop:
	s_waitcnt lgkmcnt(7)
	v_mfma_f32_16x16x32_bf16 v[128:131], v[200:203], v[96:99], 0
	v_add_f32_e32 v169, v169, v64
	v_mfma_f32_16x16x32_bf16 v[132:135], v[200:203], v[112:115], 0
	ds_read_b128 v[200:203], v174 offset:16384
	v_add_f32_e32 v169, v169, v65
	v_cvt_pk_bf16_f32 v184, v64, v65
	s_waitcnt lgkmcnt(7)
	v_mfma_f32_16x16x32_bf16 v[136:139], v[204:207], v[96:99], 0
	v_add_f32_e32 v169, v169, v66
	v_mfma_f32_16x16x32_bf16 v[140:143], v[204:207], v[112:115], 0
	ds_read_b128 v[204:207], v174 offset:20480
	v_add_f32_e32 v169, v169, v67
	v_cvt_pk_bf16_f32 v185, v66, v67
	s_waitcnt lgkmcnt(7)
	v_mfma_f32_16x16x32_bf16 v[144:147], v[208:211], v[96:99], 0
	v_add_f32_e32 v222, v222, v68
	v_mfma_f32_16x16x32_bf16 v[148:151], v[208:211], v[112:115], 0
	ds_read_b128 v[208:211], v174 offset:24576
	v_add_f32_e32 v222, v222, v69
	v_cvt_pk_bf16_f32 v186, v72, v73
	s_waitcnt lgkmcnt(7)
	v_mfma_f32_16x16x32_bf16 v[152:155], v[212:215], v[96:99], 0
	v_add_f32_e32 v222, v222, v70
	v_mfma_f32_16x16x32_bf16 v[156:159], v[212:215], v[112:115], 0
	ds_read_b128 v[212:215], v174 offset:28672
	v_add_f32_e32 v222, v222, v71
	v_cvt_pk_bf16_f32 v187, v74, v75
	s_waitcnt lgkmcnt(7)
	v_mfma_f32_16x16x32_bf16 v[128:131], v[230:233], v[100:103], v[128:131]
	v_add_f32_e32 v169, v169, v72
	v_mfma_f32_16x16x32_bf16 v[132:135], v[230:233], v[116:119], v[132:135]
	ds_read_b128 v[230:233], v175 offset:16384
	v_add_f32_e32 v169, v169, v73
	v_cvt_pk_bf16_f32 v188, v80, v81
	s_waitcnt lgkmcnt(7)
	v_mfma_f32_16x16x32_bf16 v[136:139], v[234:237], v[100:103], v[136:139]
	v_add_f32_e32 v169, v169, v74
	v_mfma_f32_16x16x32_bf16 v[140:143], v[234:237], v[116:119], v[140:143]
	ds_read_b128 v[234:237], v175 offset:20480
	v_add_f32_e32 v169, v169, v75
	v_cvt_pk_bf16_f32 v189, v82, v83
	s_waitcnt lgkmcnt(7)
	v_mfma_f32_16x16x32_bf16 v[144:147], v[238:241], v[100:103], v[144:147]
	v_add_f32_e32 v222, v222, v76
	v_mfma_f32_16x16x32_bf16 v[148:151], v[238:241], v[116:119], v[148:151]
	ds_read_b128 v[238:241], v175 offset:24576
	v_add_f32_e32 v222, v222, v77
	v_cvt_pk_bf16_f32 v190, v88, v89
	s_waitcnt lgkmcnt(7)
	v_mfma_f32_16x16x32_bf16 v[152:155], v[242:245], v[100:103], v[152:155]
	v_add_f32_e32 v222, v222, v78
	v_mfma_f32_16x16x32_bf16 v[156:159], v[242:245], v[116:119], v[156:159]
	ds_read_b128 v[242:245], v175 offset:28672
	v_add_f32_e32 v222, v222, v79
	v_cvt_pk_bf16_f32 v191, v90, v91
	s_waitcnt lgkmcnt(7)
	v_mfma_f32_16x16x32_bf16 v[128:131], v[200:203], v[104:107], v[128:131]
	v_add_f32_e32 v169, v169, v80
	s_add_i32 m0, s32, 0x0
	s_nop 0
	global_load_lds_dwordx4 v183, s[98:99]
	v_mfma_f32_16x16x32_bf16 v[132:135], v[200:203], v[120:123], v[132:135]
	v_add_f32_e32 v169, v169, v81
	v_cvt_pk_bf16_f32 v192, v68, v69
	s_waitcnt lgkmcnt(6)
	v_mfma_f32_16x16x32_bf16 v[136:139], v[204:207], v[104:107], v[136:139]
	v_add_f32_e32 v169, v169, v82
	s_add_i32 m0, s32, 0x2000
	s_nop 0
	global_load_lds_dwordx4 v183, s[100:101]
	s_add_u32 s98, s98, 0x150000
	s_addc_u32 s99, s99, 0
	s_add_u32 s100, s100, 0x150000
	s_addc_u32 s101, s101, 0
	v_mfma_f32_16x16x32_bf16 v[140:143], v[204:207], v[120:123], v[140:143]
	v_add_f32_e32 v169, v169, v83
	v_cvt_pk_bf16_f32 v193, v70, v71
	s_waitcnt lgkmcnt(5)
	v_mfma_f32_16x16x32_bf16 v[144:147], v[208:211], v[104:107], v[144:147]
	v_add_f32_e32 v222, v222, v84
	s_add_i32 m0, s32, 0x18000
	s_nop 0
	global_load_lds_dwordx4 v181, s[0:1]
	v_mfma_f32_16x16x32_bf16 v[148:151], v[208:211], v[120:123], v[148:151]
	v_add_f32_e32 v222, v222, v85
	v_cvt_pk_bf16_f32 v194, v76, v77
	s_add_i32 m0, s32, 0x1a000
	s_nop 0
	global_load_lds_dwordx4 v181, s[4:5]
	s_add_u32 s0, s0, 0x150000
	s_addc_u32 s1, s1, 0
	s_add_u32 s4, s4, 0x150000
	s_addc_u32 s5, s5, 0
	s_waitcnt lgkmcnt(4)
	v_mfma_f32_16x16x32_bf16 v[152:155], v[212:215], v[104:107], v[152:155]
	ds_read_b64_tr_b16 v[200:201], v176 offset:0
	ds_read_b64_tr_b16 v[202:203], v176 offset:4096
	v_add_f32_e32 v222, v222, v86
	v_mfma_f32_16x16x32_bf16 v[156:159], v[212:215], v[120:123], v[156:159]
	v_add_f32_e32 v222, v222, v87
	v_cvt_pk_bf16_f32 v195, v78, v79
	s_waitcnt lgkmcnt(5)
	v_mfma_f32_16x16x32_bf16 v[128:131], v[230:233], v[108:111], v[128:131]
	ds_read_b64_tr_b16 v[204:205], v177 offset:0
	ds_read_b64_tr_b16 v[206:207], v177 offset:4096
	v_add_f32_e32 v169, v169, v88
	v_mfma_f32_16x16x32_bf16 v[132:135], v[230:233], v[124:127], v[132:135]
	v_add_f32_e32 v169, v169, v89
	v_cvt_pk_bf16_f32 v196, v84, v85
	s_waitcnt lgkmcnt(6)
	v_mfma_f32_16x16x32_bf16 v[136:139], v[234:237], v[108:111], v[136:139]
	ds_read_b64_tr_b16 v[208:209], v178 offset:0
	ds_read_b64_tr_b16 v[210:211], v178 offset:4096
	v_add_f32_e32 v169, v169, v90
	v_mfma_f32_16x16x32_bf16 v[140:143], v[234:237], v[124:127], v[140:143]
	v_add_f32_e32 v169, v169, v91
	v_cvt_pk_bf16_f32 v197, v86, v87
	s_waitcnt lgkmcnt(7)
	v_mfma_f32_16x16x32_bf16 v[144:147], v[238:241], v[108:111], v[144:147]
	ds_read_b64_tr_b16 v[212:213], v179 offset:0
	ds_read_b64_tr_b16 v[214:215], v179 offset:4096
	v_add_f32_e32 v222, v222, v92
	v_mfma_f32_16x16x32_bf16 v[148:151], v[238:241], v[124:127], v[148:151]
	v_add_f32_e32 v222, v222, v93
	v_cvt_pk_bf16_f32 v198, v92, v93
	s_waitcnt lgkmcnt(8)
	v_mfma_f32_16x16x32_bf16 v[152:155], v[242:245], v[108:111], v[152:155]
	ds_read_b64_tr_b16 v[230:231], v180 offset:0
	ds_read_b64_tr_b16 v[232:233], v180 offset:4096
	v_add_f32_e32 v222, v222, v94
	v_mfma_f32_16x16x32_bf16 v[156:159], v[242:245], v[124:127], v[156:159]
	v_add_f32_e32 v222, v222, v95
	v_cvt_pk_bf16_f32 v199, v94, v95
	s_waitcnt lgkmcnt(8)
; __device__ __forceinline__ void partialSM(f32x16& p0, f32x16& p1, float& m_reg, float& mn, float& alpha) {
;     ...
;   for (int r = 0; r < 16; ++r) p0[r] = __builtin_amdgcn_exp2f(p0[r]);
; }
; __device__ __forceinline__ void finishSM(f32x16& p0, f32x16& p1, float alpha, float& l_reg, bf16x8& pa0, bf16x8& pa1, bf16x8& pa2, bf16x8& pa3) {
; #pragma unroll
;   for (int r = 0; r < 16; ++r) p1[r] = __builtin_amdgcn_exp2f(p1[r]);
;   float ps = 0;
; #pragma unroll
;   for (int r = 0; r < 16; ++r) ps += p0[r];
; #pragma unroll
;   for (int r = 0; r < 16; ++r) ps += p1[r];
;   { auto rr = __builtin_amdgcn_permlane32_swap(__float_as_uint(ps), __float_as_uint(ps), false, false);
;     ps = __uint_as_float(rr[0]) + __uint_as_float(rr[1]); }
;   l_reg = l_reg * alpha + ps;
;     ...
;   PK4(p0, 0, pa0); PK4(p0, 8, pa1); PK4(p1, 0, pa2); PK4(p1, 8, pa3);
;     ...
; }
; __device__ __forceinline__ void qkt(f32x16& p0, f32x16& p1, const bf16* Ks, const bf16x8* qr, int r32, int hi) {
;   p0 = f32x16{}; p1 = f32x16{};
; #pragma unroll
;   for (int d0 = 0; d0 < 8; ++d0) { int cb = (d0 * 16 + hi * 8) * 2;
;     bf16x8 b0 = *reinterpret_cast<const bf16x8*>((const char*)Ks + KSWZ(r32, cb));
;     bf16x8 b1 = *reinterpret_cast<const bf16x8*>((const char*)Ks + KSWZ(32 + r32, cb));
;     p0 = __builtin_amdgcn_mfma_f32_32x32x16_bf16(b0, qr[d0], p0, 0, 0, 0);
;     p1 = __builtin_amdgcn_mfma_f32_32x32x16_bf16(b1, qr[d0], p1, 0, 0, 0); }
; }
; __device__ __forceinline__ int v_st(int k, int c) { const int kk = (k & ~0xC) | ((k & 4) << 1) | ((k & 8) >> 1); return ((kk >> 3) * 4 + (c >> 5)) * 512 + ((kk & 7) * 32 + (c & 31)) * 2; }
; __device__ __forceinline__ int v_rd_base(int lane) { return ((lane & 3) << 3) | (((lane >> 2) & 3) << 6) | (((lane >> 4) & 1) << 5) | (((lane >> 5) & 1) << 8); }
; template <int OFF> __device__ __forceinline__ s16x4 tr_read(int vb) {
;   s16x4 r; asm volatile("ds_read_b64_tr_b16 %0, %1 offset:%2" : "=&v"(r) : "v"(vb), "i"(OFF) : "memory"); return r;
; }
; template <int D0> __device__ __forceinline__ void pv_one(f32x16& od, int vb, bf16x8 pa0, bf16x8 pa1, bf16x8 pa2, bf16x8 pa3) {
;   const s16x4 l0 = tr_read<v_rd_off(D0, 0, 0)>(vb), h0 = tr_read<v_rd_off(D0, 0, 1)>(vb), l1 = tr_read<v_rd_off(D0, 1, 0)>(vb), h1 = tr_read<v_rd_off(D0, 1, 1)>(vb);
	v_mfma_f32_16x16x32_bf16 v[0:3], v[200:203], v[184:187], v[0:3]
	v_exp_f32_e32 v128, v128
	v_mfma_f32_16x16x32_bf16 v[32:35], v[200:203], v[192:195], v[32:35]
	ds_read_b64_tr_b16 v[234:235], v182 offset:0
	ds_read_b64_tr_b16 v[236:237], v182 offset:4096
	v_exp_f32_e32 v129, v129
	s_waitcnt lgkmcnt(8)
	v_mfma_f32_16x16x32_bf16 v[4:7], v[204:207], v[184:187], v[4:7]
	v_exp_f32_e32 v130, v130
	v_mfma_f32_16x16x32_bf16 v[36:39], v[204:207], v[192:195], v[36:39]
	ds_read_b64_tr_b16 v[238:239], v216 offset:0
	ds_read_b64_tr_b16 v[240:241], v216 offset:4096
	v_exp_f32_e32 v131, v131
	s_waitcnt lgkmcnt(8)
	v_mfma_f32_16x16x32_bf16 v[8:11], v[208:211], v[184:187], v[8:11]
	v_exp_f32_e32 v132, v132
	v_mfma_f32_16x16x32_bf16 v[40:43], v[208:211], v[192:195], v[40:43]
	ds_read_b64_tr_b16 v[242:243], v217 offset:0
	ds_read_b64_tr_b16 v[244:245], v217 offset:4096
	v_exp_f32_e32 v133, v133
	s_waitcnt lgkmcnt(8)
	v_mfma_f32_16x16x32_bf16 v[12:15], v[212:215], v[184:187], v[12:15]
	v_exp_f32_e32 v134, v134
	v_mfma_f32_16x16x32_bf16 v[44:47], v[212:215], v[192:195], v[44:47]
	ds_read_b64_tr_b16 v[200:201], v176 offset:8192
	ds_read_b64_tr_b16 v[202:203], v176 offset:12288
	v_exp_f32_e32 v135, v135
	s_waitcnt lgkmcnt(8)
	v_mfma_f32_16x16x32_bf16 v[16:19], v[230:233], v[184:187], v[16:19]
	v_exp_f32_e32 v136, v136
	v_mfma_f32_16x16x32_bf16 v[48:51], v[230:233], v[192:195], v[48:51]
	ds_read_b64_tr_b16 v[204:205], v177 offset:8192
	ds_read_b64_tr_b16 v[206:207], v177 offset:12288
	v_exp_f32_e32 v137, v137
	s_waitcnt lgkmcnt(8)
	v_mfma_f32_16x16x32_bf16 v[20:23], v[234:237], v[184:187], v[20:23]
	v_exp_f32_e32 v138, v138
	v_mfma_f32_16x16x32_bf16 v[52:55], v[234:237], v[192:195], v[52:55]
	ds_read_b64_tr_b16 v[208:209], v178 offset:8192
	ds_read_b64_tr_b16 v[210:211], v178 offset:12288
	v_exp_f32_e32 v139, v139
	s_waitcnt lgkmcnt(8)
	v_mfma_f32_16x16x32_bf16 v[24:27], v[238:241], v[184:187], v[24:27]
	v_exp_f32_e32 v140, v140
	v_mfma_f32_16x16x32_bf16 v[56:59], v[238:241], v[192:195], v[56:59]
	ds_read_b64_tr_b16 v[212:213], v179 offset:8192
	ds_read_b64_tr_b16 v[214:215], v179 offset:12288
	v_exp_f32_e32 v141, v141
	s_waitcnt lgkmcnt(8)
	v_mfma_f32_16x16x32_bf16 v[28:31], v[242:245], v[184:187], v[28:31]
	v_exp_f32_e32 v142, v142
	v_mfma_f32_16x16x32_bf16 v[60:63], v[242:245], v[192:195], v[60:63]
	ds_read_b64_tr_b16 v[230:231], v180 offset:8192
	ds_read_b64_tr_b16 v[232:233], v180 offset:12288
	v_exp_f32_e32 v143, v143
	s_waitcnt lgkmcnt(8)
	v_mfma_f32_16x16x32_bf16 v[0:3], v[200:203], v[188:191], v[0:3]
	v_exp_f32_e32 v144, v144
	v_mfma_f32_16x16x32_bf16 v[32:35], v[200:203], v[196:199], v[32:35]
	ds_read_b64_tr_b16 v[234:235], v182 offset:8192
	ds_read_b64_tr_b16 v[236:237], v182 offset:12288
	ds_read_b128 v[200:203], v172 offset:32768
	v_exp_f32_e32 v145, v145
	s_waitcnt lgkmcnt(9)
	v_mfma_f32_16x16x32_bf16 v[4:7], v[204:207], v[188:191], v[4:7]
	v_exp_f32_e32 v146, v146
	v_mfma_f32_16x16x32_bf16 v[36:39], v[204:207], v[196:199], v[36:39]
	ds_read_b64_tr_b16 v[238:239], v216 offset:8192
	ds_read_b64_tr_b16 v[240:241], v216 offset:12288
	ds_read_b128 v[204:207], v172 offset:36864
	v_exp_f32_e32 v147, v147
	s_waitcnt lgkmcnt(10)
	v_mfma_f32_16x16x32_bf16 v[8:11], v[208:211], v[188:191], v[8:11]
	v_exp_f32_e32 v148, v148
	v_mfma_f32_16x16x32_bf16 v[40:43], v[208:211], v[196:199], v[40:43]
	ds_read_b64_tr_b16 v[242:243], v217 offset:8192
	ds_read_b64_tr_b16 v[244:245], v217 offset:12288
	ds_read_b128 v[208:211], v172 offset:40960
	v_exp_f32_e32 v149, v149
	s_waitcnt lgkmcnt(11)
	v_mfma_f32_16x16x32_bf16 v[12:15], v[212:215], v[188:191], v[12:15]
	v_exp_f32_e32 v150, v150
	v_mfma_f32_16x16x32_bf16 v[44:47], v[212:215], v[196:199], v[44:47]
	ds_read_b128 v[212:215], v172 offset:45056
	v_exp_f32_e32 v151, v151
	s_waitcnt lgkmcnt(10)
	v_mfma_f32_16x16x32_bf16 v[16:19], v[230:233], v[188:191], v[16:19]
	v_exp_f32_e32 v152, v152
	v_mfma_f32_16x16x32_bf16 v[48:51], v[230:233], v[196:199], v[48:51]
	ds_read_b128 v[230:233], v173 offset:32768
	v_exp_f32_e32 v153, v153
	s_waitcnt lgkmcnt(9)
	v_mfma_f32_16x16x32_bf16 v[20:23], v[234:237], v[188:191], v[20:23]
	v_exp_f32_e32 v154, v154
	v_mfma_f32_16x16x32_bf16 v[52:55], v[234:237], v[196:199], v[52:55]
	ds_read_b128 v[234:237], v173 offset:36864
	v_exp_f32_e32 v155, v155
	s_waitcnt lgkmcnt(7)
	v_mfma_f32_16x16x32_bf16 v[24:27], v[238:241], v[188:191], v[24:27]
	v_exp_f32_e32 v156, v156
	v_mfma_f32_16x16x32_bf16 v[56:59], v[238:241], v[196:199], v[56:59]
	ds_read_b128 v[238:241], v173 offset:40960
	v_exp_f32_e32 v157, v157
	s_waitcnt lgkmcnt(5)
	v_mfma_f32_16x16x32_bf16 v[28:31], v[242:245], v[188:191], v[28:31]
	v_exp_f32_e32 v158, v158
	v_mfma_f32_16x16x32_bf16 v[60:63], v[242:245], v[196:199], v[60:63]
	ds_read_b128 v[242:245], v173 offset:45056
	v_exp_f32_e32 v159, v159
	s_waitcnt vmcnt(4)
	s_barrier
; __device__ __forceinline__ void partialSM(f32x16& p0, f32x16& p1, float& m_reg, float& mn, float& alpha) {
;     ...
;   for (int r = 0; r < 16; ++r) p0[r] = __builtin_amdgcn_exp2f(p0[r]);
; }
; __device__ __forceinline__ void finishSM(f32x16& p0, f32x16& p1, float alpha, float& l_reg, bf16x8& pa0, bf16x8& pa1, bf16x8& pa2, bf16x8& pa3) {
; #pragma unroll
;   for (int r = 0; r < 16; ++r) p1[r] = __builtin_amdgcn_exp2f(p1[r]);
;   float ps = 0;
; #pragma unroll
;   for (int r = 0; r < 16; ++r) ps += p0[r];
; #pragma unroll
;   for (int r = 0; r < 16; ++r) ps += p1[r];
;   { auto rr = __builtin_amdgcn_permlane32_swap(__float_as_uint(ps), __float_as_uint(ps), false, false);
;     ps = __uint_as_float(rr[0]) + __uint_as_float(rr[1]); }
;   l_reg = l_reg * alpha + ps;
;     ...
;   PK4(p0, 0, pa0); PK4(p0, 8, pa1); PK4(p1, 0, pa2); PK4(p1, 8, pa3);
;     ...
; }
; __device__ __forceinline__ void qkt(f32x16& p0, f32x16& p1, const bf16* Ks, const bf16x8* qr, int r32, int hi) {
;   p0 = f32x16{}; p1 = f32x16{};
; #pragma unroll
;   for (int d0 = 0; d0 < 8; ++d0) { int cb = (d0 * 16 + hi * 8) * 2;
;     bf16x8 b0 = *reinterpret_cast<const bf16x8*>((const char*)Ks + KSWZ(r32, cb));
;     bf16x8 b1 = *reinterpret_cast<const bf16x8*>((const char*)Ks + KSWZ(32 + r32, cb));
;     p0 = __builtin_amdgcn_mfma_f32_32x32x16_bf16(b0, qr[d0], p0, 0, 0, 0);
;     p1 = __builtin_amdgcn_mfma_f32_32x32x16_bf16(b1, qr[d0], p1, 0, 0, 0); }
; }
; __device__ __forceinline__ int v_st(int k, int c) { const int kk = (k & ~0xC) | ((k & 4) << 1) | ((k & 8) >> 1); return ((kk >> 3) * 4 + (c >> 5)) * 512 + ((kk & 7) * 32 + (c & 31)) * 2; }
; __device__ __forceinline__ int v_rd_base(int lane) { return ((lane & 3) << 3) | (((lane >> 2) & 3) << 6) | (((lane >> 4) & 1) << 5) | (((lane >> 5) & 1) << 8); }
; template <int OFF> __device__ __forceinline__ s16x4 tr_read(int vb) {
;   s16x4 r; asm volatile("ds_read_b64_tr_b16 %0, %1 offset:%2" : "=&v"(r) : "v"(vb), "i"(OFF) : "memory"); return r;
; }
; template <int D0> __device__ __forceinline__ void pv_one(f32x16& od, int vb, bf16x8 pa0, bf16x8 pa1, bf16x8 pa2, bf16x8 pa3) {
;   const s16x4 l0 = tr_read<v_rd_off(D0, 0, 0)>(vb), h0 = tr_read<v_rd_off(D0, 0, 1)>(vb), l1 = tr_read<v_rd_off(D0, 1, 0)>(vb), h1 = tr_read<v_rd_off(D0, 1, 1)>(vb);
	v_mfma_f32_16x16x32_bf16 v[64:67], v[200:203], v[96:99], 0
	v_add_f32_e32 v169, v169, v128
	v_mfma_f32_16x16x32_bf16 v[68:71], v[200:203], v[112:115], 0
	ds_read_b128 v[200:203], v174 offset:32768
	v_add_f32_e32 v169, v169, v129
	v_cvt_pk_bf16_f32 v184, v128, v129
	v_mfma_f32_16x16x32_bf16 v[72:75], v[204:207], v[96:99], 0
	v_add_f32_e32 v169, v169, v130
	v_mfma_f32_16x16x32_bf16 v[76:79], v[204:207], v[112:115], 0
	ds_read_b128 v[204:207], v174 offset:36864
	v_add_f32_e32 v169, v169, v131
	v_cvt_pk_bf16_f32 v185, v130, v131
	s_waitcnt lgkmcnt(7)
	v_mfma_f32_16x16x32_bf16 v[80:83], v[208:211], v[96:99], 0
	v_add_f32_e32 v222, v222, v132
	v_mfma_f32_16x16x32_bf16 v[84:87], v[208:211], v[112:115], 0
	ds_read_b128 v[208:211], v174 offset:40960
	v_add_f32_e32 v222, v222, v133
	v_cvt_pk_bf16_f32 v186, v136, v137
	s_waitcnt lgkmcnt(7)
	v_mfma_f32_16x16x32_bf16 v[88:91], v[212:215], v[96:99], 0
	v_add_f32_e32 v222, v222, v134
	v_mfma_f32_16x16x32_bf16 v[92:95], v[212:215], v[112:115], 0
	ds_read_b128 v[212:215], v174 offset:45056
	v_add_f32_e32 v222, v222, v135
	v_cvt_pk_bf16_f32 v187, v138, v139
	s_waitcnt lgkmcnt(7)
	v_mfma_f32_16x16x32_bf16 v[64:67], v[230:233], v[100:103], v[64:67]
	v_add_f32_e32 v169, v169, v136
	v_mfma_f32_16x16x32_bf16 v[68:71], v[230:233], v[116:119], v[68:71]
	ds_read_b128 v[230:233], v175 offset:32768
	v_add_f32_e32 v169, v169, v137
	v_cvt_pk_bf16_f32 v188, v144, v145
	s_waitcnt lgkmcnt(7)
	v_mfma_f32_16x16x32_bf16 v[72:75], v[234:237], v[100:103], v[72:75]
	v_add_f32_e32 v169, v169, v138
	v_mfma_f32_16x16x32_bf16 v[76:79], v[234:237], v[116:119], v[76:79]
	ds_read_b128 v[234:237], v175 offset:36864
	v_add_f32_e32 v169, v169, v139
	v_cvt_pk_bf16_f32 v189, v146, v147
	s_waitcnt lgkmcnt(7)
	v_mfma_f32_16x16x32_bf16 v[80:83], v[238:241], v[100:103], v[80:83]
	v_add_f32_e32 v222, v222, v140
	v_mfma_f32_16x16x32_bf16 v[84:87], v[238:241], v[116:119], v[84:87]
	ds_read_b128 v[238:241], v175 offset:40960
	v_add_f32_e32 v222, v222, v141
	v_cvt_pk_bf16_f32 v190, v152, v153
	s_waitcnt lgkmcnt(7)
	v_mfma_f32_16x16x32_bf16 v[88:91], v[242:245], v[100:103], v[88:91]
	v_add_f32_e32 v222, v222, v142
	v_mfma_f32_16x16x32_bf16 v[92:95], v[242:245], v[116:119], v[92:95]
	ds_read_b128 v[242:245], v175 offset:45056
	v_add_f32_e32 v222, v222, v143
	v_cvt_pk_bf16_f32 v191, v154, v155
	s_waitcnt lgkmcnt(7)
	v_mfma_f32_16x16x32_bf16 v[64:67], v[200:203], v[104:107], v[64:67]
	v_add_f32_e32 v169, v169, v144
	s_add_i32 m0, s32, 0x4000
	s_nop 0
	global_load_lds_dwordx4 v183, s[98:99]
	v_mfma_f32_16x16x32_bf16 v[68:71], v[200:203], v[120:123], v[68:71]
	v_add_f32_e32 v169, v169, v145
	v_cvt_pk_bf16_f32 v192, v132, v133
	s_waitcnt lgkmcnt(6)
	v_mfma_f32_16x16x32_bf16 v[72:75], v[204:207], v[104:107], v[72:75]
	v_add_f32_e32 v169, v169, v146
	s_add_i32 m0, s32, 0x6000
	s_nop 0
	global_load_lds_dwordx4 v183, s[100:101]
	s_add_u32 s98, s98, 0x150000
	s_addc_u32 s99, s99, 0
	s_add_u32 s100, s100, 0x150000
	s_addc_u32 s101, s101, 0
	v_mfma_f32_16x16x32_bf16 v[76:79], v[204:207], v[120:123], v[76:79]
	v_add_f32_e32 v169, v169, v147
	v_cvt_pk_bf16_f32 v193, v134, v135
	s_waitcnt lgkmcnt(5)
	v_mfma_f32_16x16x32_bf16 v[80:83], v[208:211], v[104:107], v[80:83]
	v_add_f32_e32 v222, v222, v148
	s_add_i32 m0, s32, 0x1c000
	s_nop 0
	global_load_lds_dwordx4 v181, s[0:1]
	v_mfma_f32_16x16x32_bf16 v[84:87], v[208:211], v[120:123], v[84:87]
	v_add_f32_e32 v222, v222, v149
	v_cvt_pk_bf16_f32 v194, v140, v141
	s_add_i32 m0, s32, 0x1e000
	s_nop 0
	global_load_lds_dwordx4 v181, s[4:5]
	s_add_u32 s0, s0, 0x150000
	s_addc_u32 s1, s1, 0
	s_add_u32 s4, s4, 0x150000
	s_addc_u32 s5, s5, 0
	s_waitcnt lgkmcnt(4)
	v_mfma_f32_16x16x32_bf16 v[88:91], v[212:215], v[104:107], v[88:91]
	ds_read_b64_tr_b16 v[200:201], v176 offset:16384
	ds_read_b64_tr_b16 v[202:203], v176 offset:20480
	v_add_f32_e32 v222, v222, v150
	v_mfma_f32_16x16x32_bf16 v[92:95], v[212:215], v[120:123], v[92:95]
	v_add_f32_e32 v222, v222, v151
	v_cvt_pk_bf16_f32 v195, v142, v143
	s_waitcnt lgkmcnt(5)
	v_mfma_f32_16x16x32_bf16 v[64:67], v[230:233], v[108:111], v[64:67]
	ds_read_b64_tr_b16 v[204:205], v177 offset:16384
	ds_read_b64_tr_b16 v[206:207], v177 offset:20480
	v_add_f32_e32 v169, v169, v152
	v_mfma_f32_16x16x32_bf16 v[68:71], v[230:233], v[124:127], v[68:71]
	v_add_f32_e32 v169, v169, v153
	v_cvt_pk_bf16_f32 v196, v148, v149
	s_waitcnt lgkmcnt(6)
	v_mfma_f32_16x16x32_bf16 v[72:75], v[234:237], v[108:111], v[72:75]
	ds_read_b64_tr_b16 v[208:209], v178 offset:16384
	ds_read_b64_tr_b16 v[210:211], v178 offset:20480
	v_add_f32_e32 v169, v169, v154
	v_mfma_f32_16x16x32_bf16 v[76:79], v[234:237], v[124:127], v[76:79]
	v_add_f32_e32 v169, v169, v155
	v_cvt_pk_bf16_f32 v197, v150, v151
	s_waitcnt lgkmcnt(7)
	v_mfma_f32_16x16x32_bf16 v[80:83], v[238:241], v[108:111], v[80:83]
	ds_read_b64_tr_b16 v[212:213], v179 offset:16384
	ds_read_b64_tr_b16 v[214:215], v179 offset:20480
	v_add_f32_e32 v222, v222, v156
	v_mfma_f32_16x16x32_bf16 v[84:87], v[238:241], v[124:127], v[84:87]
	v_add_f32_e32 v222, v222, v157
	v_cvt_pk_bf16_f32 v198, v156, v157
	s_waitcnt lgkmcnt(8)
	v_mfma_f32_16x16x32_bf16 v[88:91], v[242:245], v[108:111], v[88:91]
	ds_read_b64_tr_b16 v[230:231], v180 offset:16384
	ds_read_b64_tr_b16 v[232:233], v180 offset:20480
	v_add_f32_e32 v222, v222, v158
	v_mfma_f32_16x16x32_bf16 v[92:95], v[242:245], v[124:127], v[92:95]
	v_add_f32_e32 v222, v222, v159
	v_cvt_pk_bf16_f32 v199, v158, v159
	s_waitcnt lgkmcnt(8)
	v_mfma_f32_16x16x32_bf16 v[0:3], v[200:203], v[184:187], v[0:3]
	v_exp_f32_e32 v64, v64
	v_mfma_f32_16x16x32_bf16 v[32:35], v[200:203], v[192:195], v[32:35]
	ds_read_b64_tr_b16 v[234:235], v182 offset:16384
	ds_read_b64_tr_b16 v[236:237], v182 offset:20480
	v_exp_f32_e32 v65, v65
	s_waitcnt lgkmcnt(8)
; __device__ __forceinline__ void partialSM(f32x16& p0, f32x16& p1, float& m_reg, float& mn, float& alpha) {
;     ...
;   for (int r = 0; r < 16; ++r) p0[r] = __builtin_amdgcn_exp2f(p0[r]);
; }
; __device__ __forceinline__ void finishSM(f32x16& p0, f32x16& p1, float alpha, float& l_reg, bf16x8& pa0, bf16x8& pa1, bf16x8& pa2, bf16x8& pa3) {
; #pragma unroll
;   for (int r = 0; r < 16; ++r) p1[r] = __builtin_amdgcn_exp2f(p1[r]);
;   float ps = 0;
; #pragma unroll
;   for (int r = 0; r < 16; ++r) ps += p0[r];
; #pragma unroll
;   for (int r = 0; r < 16; ++r) ps += p1[r];
;   { auto rr = __builtin_amdgcn_permlane32_swap(__float_as_uint(ps), __float_as_uint(ps), false, false);
;     ps = __uint_as_float(rr[0]) + __uint_as_float(rr[1]); }
;   l_reg = l_reg * alpha + ps;
;     ...
;   PK4(p0, 0, pa0); PK4(p0, 8, pa1); PK4(p1, 0, pa2); PK4(p1, 8, pa3);
;     ...
; }
; __device__ __forceinline__ void qkt(f32x16& p0, f32x16& p1, const bf16* Ks, const bf16x8* qr, int r32, int hi) {
;   p0 = f32x16{}; p1 = f32x16{};
; #pragma unroll
;   for (int d0 = 0; d0 < 8; ++d0) { int cb = (d0 * 16 + hi * 8) * 2;
;     bf16x8 b0 = *reinterpret_cast<const bf16x8*>((const char*)Ks + KSWZ(r32, cb));
;     bf16x8 b1 = *reinterpret_cast<const bf16x8*>((const char*)Ks + KSWZ(32 + r32, cb));
;     p0 = __builtin_amdgcn_mfma_f32_32x32x16_bf16(b0, qr[d0], p0, 0, 0, 0);
;     p1 = __builtin_amdgcn_mfma_f32_32x32x16_bf16(b1, qr[d0], p1, 0, 0, 0); }
; }
; __device__ __forceinline__ int v_st(int k, int c) { const int kk = (k & ~0xC) | ((k & 4) << 1) | ((k & 8) >> 1); return ((kk >> 3) * 4 + (c >> 5)) * 512 + ((kk & 7) * 32 + (c & 31)) * 2; }
; __device__ __forceinline__ int v_rd_base(int lane) { return ((lane & 3) << 3) | (((lane >> 2) & 3) << 6) | (((lane >> 4) & 1) << 5) | (((lane >> 5) & 1) << 8); }
; template <int OFF> __device__ __forceinline__ s16x4 tr_read(int vb) {
;   s16x4 r; asm volatile("ds_read_b64_tr_b16 %0, %1 offset:%2" : "=&v"(r) : "v"(vb), "i"(OFF) : "memory"); return r;
; }
; template <int D0> __device__ __forceinline__ void pv_one(f32x16& od, int vb, bf16x8 pa0, bf16x8 pa1, bf16x8 pa2, bf16x8 pa3) {
;   const s16x4 l0 = tr_read<v_rd_off(D0, 0, 0)>(vb), h0 = tr_read<v_rd_off(D0, 0, 1)>(vb), l1 = tr_read<v_rd_off(D0, 1, 0)>(vb), h1 = tr_read<v_rd_off(D0, 1, 1)>(vb);
	v_mfma_f32_16x16x32_bf16 v[4:7], v[204:207], v[184:187], v[4:7]
	v_exp_f32_e32 v66, v66
	v_mfma_f32_16x16x32_bf16 v[36:39], v[204:207], v[192:195], v[36:39]
	ds_read_b64_tr_b16 v[238:239], v216 offset:16384
	ds_read_b64_tr_b16 v[240:241], v216 offset:20480
	v_exp_f32_e32 v67, v67
	s_waitcnt lgkmcnt(8)
	v_mfma_f32_16x16x32_bf16 v[8:11], v[208:211], v[184:187], v[8:11]
	v_exp_f32_e32 v68, v68
	v_mfma_f32_16x16x32_bf16 v[40:43], v[208:211], v[192:195], v[40:43]
	ds_read_b64_tr_b16 v[242:243], v217 offset:16384
	ds_read_b64_tr_b16 v[244:245], v217 offset:20480
	v_exp_f32_e32 v69, v69
	s_waitcnt lgkmcnt(8)
	v_mfma_f32_16x16x32_bf16 v[12:15], v[212:215], v[184:187], v[12:15]
	v_exp_f32_e32 v70, v70
	v_mfma_f32_16x16x32_bf16 v[44:47], v[212:215], v[192:195], v[44:47]
	ds_read_b64_tr_b16 v[200:201], v176 offset:24576
	ds_read_b64_tr_b16 v[202:203], v176 offset:28672
	v_exp_f32_e32 v71, v71
	s_waitcnt lgkmcnt(8)
	v_mfma_f32_16x16x32_bf16 v[16:19], v[230:233], v[184:187], v[16:19]
	v_exp_f32_e32 v72, v72
	v_mfma_f32_16x16x32_bf16 v[48:51], v[230:233], v[192:195], v[48:51]
	ds_read_b64_tr_b16 v[204:205], v177 offset:24576
	ds_read_b64_tr_b16 v[206:207], v177 offset:28672
	v_exp_f32_e32 v73, v73
	s_waitcnt lgkmcnt(8)
	v_mfma_f32_16x16x32_bf16 v[20:23], v[234:237], v[184:187], v[20:23]
	v_exp_f32_e32 v74, v74
	v_mfma_f32_16x16x32_bf16 v[52:55], v[234:237], v[192:195], v[52:55]
	ds_read_b64_tr_b16 v[208:209], v178 offset:24576
	ds_read_b64_tr_b16 v[210:211], v178 offset:28672
	v_exp_f32_e32 v75, v75
	s_waitcnt lgkmcnt(8)
	v_mfma_f32_16x16x32_bf16 v[24:27], v[238:241], v[184:187], v[24:27]
	v_exp_f32_e32 v76, v76
	v_mfma_f32_16x16x32_bf16 v[56:59], v[238:241], v[192:195], v[56:59]
	ds_read_b64_tr_b16 v[212:213], v179 offset:24576
	ds_read_b64_tr_b16 v[214:215], v179 offset:28672
	v_exp_f32_e32 v77, v77
	s_waitcnt lgkmcnt(8)
	v_mfma_f32_16x16x32_bf16 v[28:31], v[242:245], v[184:187], v[28:31]
	v_exp_f32_e32 v78, v78
	v_mfma_f32_16x16x32_bf16 v[60:63], v[242:245], v[192:195], v[60:63]
	ds_read_b64_tr_b16 v[230:231], v180 offset:24576
	ds_read_b64_tr_b16 v[232:233], v180 offset:28672
	v_exp_f32_e32 v79, v79
	s_waitcnt lgkmcnt(8)
	v_mfma_f32_16x16x32_bf16 v[0:3], v[200:203], v[188:191], v[0:3]
	v_exp_f32_e32 v80, v80
	v_mfma_f32_16x16x32_bf16 v[32:35], v[200:203], v[196:199], v[32:35]
	ds_read_b64_tr_b16 v[234:235], v182 offset:24576
	ds_read_b64_tr_b16 v[236:237], v182 offset:28672
	ds_read_b128 v[200:203], v172 offset:49152
	v_exp_f32_e32 v81, v81
	s_waitcnt lgkmcnt(9)
	v_mfma_f32_16x16x32_bf16 v[4:7], v[204:207], v[188:191], v[4:7]
	v_exp_f32_e32 v82, v82
	v_mfma_f32_16x16x32_bf16 v[36:39], v[204:207], v[196:199], v[36:39]
	ds_read_b64_tr_b16 v[238:239], v216 offset:24576
	ds_read_b64_tr_b16 v[240:241], v216 offset:28672
	ds_read_b128 v[204:207], v172 offset:53248
	v_exp_f32_e32 v83, v83
	s_waitcnt lgkmcnt(10)
	v_mfma_f32_16x16x32_bf16 v[8:11], v[208:211], v[188:191], v[8:11]
	v_exp_f32_e32 v84, v84
	v_mfma_f32_16x16x32_bf16 v[40:43], v[208:211], v[196:199], v[40:43]
	ds_read_b64_tr_b16 v[242:243], v217 offset:24576
	ds_read_b64_tr_b16 v[244:245], v217 offset:28672
	ds_read_b128 v[208:211], v172 offset:57344
	v_exp_f32_e32 v85, v85
	s_waitcnt lgkmcnt(11)
	v_mfma_f32_16x16x32_bf16 v[12:15], v[212:215], v[188:191], v[12:15]
	v_exp_f32_e32 v86, v86
	v_mfma_f32_16x16x32_bf16 v[44:47], v[212:215], v[196:199], v[44:47]
	ds_read_b128 v[212:215], v172 offset:61440
	v_exp_f32_e32 v87, v87
	s_waitcnt lgkmcnt(10)
	v_mfma_f32_16x16x32_bf16 v[16:19], v[230:233], v[188:191], v[16:19]
	v_exp_f32_e32 v88, v88
	v_mfma_f32_16x16x32_bf16 v[48:51], v[230:233], v[196:199], v[48:51]
	ds_read_b128 v[230:233], v173 offset:49152
	v_exp_f32_e32 v89, v89
	s_waitcnt lgkmcnt(9)
	v_mfma_f32_16x16x32_bf16 v[20:23], v[234:237], v[188:191], v[20:23]
	v_exp_f32_e32 v90, v90
	v_mfma_f32_16x16x32_bf16 v[52:55], v[234:237], v[196:199], v[52:55]
	ds_read_b128 v[234:237], v173 offset:53248
	v_exp_f32_e32 v91, v91
	s_waitcnt lgkmcnt(7)
	v_mfma_f32_16x16x32_bf16 v[24:27], v[238:241], v[188:191], v[24:27]
	v_exp_f32_e32 v92, v92
	v_mfma_f32_16x16x32_bf16 v[56:59], v[238:241], v[196:199], v[56:59]
	ds_read_b128 v[238:241], v173 offset:57344
	v_exp_f32_e32 v93, v93
	s_waitcnt lgkmcnt(5)
	v_mfma_f32_16x16x32_bf16 v[28:31], v[242:245], v[188:191], v[28:31]
	v_exp_f32_e32 v94, v94
	v_mfma_f32_16x16x32_bf16 v[60:63], v[242:245], v[196:199], v[60:63]
	ds_read_b128 v[242:245], v173 offset:61440
	v_exp_f32_e32 v95, v95
	s_waitcnt vmcnt(4)
	s_barrier
; __device__ __forceinline__ void partialSM(f32x16& p0, f32x16& p1, float& m_reg, float& mn, float& alpha) {
;     ...
;   for (int r = 0; r < 16; ++r) p0[r] = __builtin_amdgcn_exp2f(p0[r]);
; }
; __device__ __forceinline__ void finishSM(f32x16& p0, f32x16& p1, float alpha, float& l_reg, bf16x8& pa0, bf16x8& pa1, bf16x8& pa2, bf16x8& pa3) {
; #pragma unroll
;   for (int r = 0; r < 16; ++r) p1[r] = __builtin_amdgcn_exp2f(p1[r]);
;   float ps = 0;
; #pragma unroll
;   for (int r = 0; r < 16; ++r) ps += p0[r];
; #pragma unroll
;   for (int r = 0; r < 16; ++r) ps += p1[r];
;   { auto rr = __builtin_amdgcn_permlane32_swap(__float_as_uint(ps), __float_as_uint(ps), false, false);
;     ps = __uint_as_float(rr[0]) + __uint_as_float(rr[1]); }
;   l_reg = l_reg * alpha + ps;
;     ...
;   PK4(p0, 0, pa0); PK4(p0, 8, pa1); PK4(p1, 0, pa2); PK4(p1, 8, pa3);
;     ...
; }
; __device__ __forceinline__ void qkt(f32x16& p0, f32x16& p1, const bf16* Ks, const bf16x8* qr, int r32, int hi) {
;   p0 = f32x16{}; p1 = f32x16{};
; #pragma unroll
;   for (int d0 = 0; d0 < 8; ++d0) { int cb = (d0 * 16 + hi * 8) * 2;
;     bf16x8 b0 = *reinterpret_cast<const bf16x8*>((const char*)Ks + KSWZ(r32, cb));
;     bf16x8 b1 = *reinterpret_cast<const bf16x8*>((const char*)Ks + KSWZ(32 + r32, cb));
;     p0 = __builtin_amdgcn_mfma_f32_32x32x16_bf16(b0, qr[d0], p0, 0, 0, 0);
;     p1 = __builtin_amdgcn_mfma_f32_32x32x16_bf16(b1, qr[d0], p1, 0, 0, 0); }
; }
; __device__ __forceinline__ int v_st(int k, int c) { const int kk = (k & ~0xC) | ((k & 4) << 1) | ((k & 8) >> 1); return ((kk >> 3) * 4 + (c >> 5)) * 512 + ((kk & 7) * 32 + (c & 31)) * 2; }
; __device__ __forceinline__ int v_rd_base(int lane) { return ((lane & 3) << 3) | (((lane >> 2) & 3) << 6) | (((lane >> 4) & 1) << 5) | (((lane >> 5) & 1) << 8); }
; template <int OFF> __device__ __forceinline__ s16x4 tr_read(int vb) {
;   s16x4 r; asm volatile("ds_read_b64_tr_b16 %0, %1 offset:%2" : "=&v"(r) : "v"(vb), "i"(OFF) : "memory"); return r;
; }
; template <int D0> __device__ __forceinline__ void pv_one(f32x16& od, int vb, bf16x8 pa0, bf16x8 pa1, bf16x8 pa2, bf16x8 pa3) {
;   const s16x4 l0 = tr_read<v_rd_off(D0, 0, 0)>(vb), h0 = tr_read<v_rd_off(D0, 0, 1)>(vb), l1 = tr_read<v_rd_off(D0, 1, 0)>(vb), h1 = tr_read<v_rd_off(D0, 1, 1)>(vb);
	v_mfma_f32_16x16x32_bf16 v[128:131], v[200:203], v[96:99], 0
	v_add_f32_e32 v169, v169, v64
	v_mfma_f32_16x16x32_bf16 v[132:135], v[200:203], v[112:115], 0
	ds_read_b128 v[200:203], v174 offset:49152
	v_add_f32_e32 v169, v169, v65
	v_cvt_pk_bf16_f32 v184, v64, v65
	v_mfma_f32_16x16x32_bf16 v[136:139], v[204:207], v[96:99], 0
	v_add_f32_e32 v169, v169, v66
	v_mfma_f32_16x16x32_bf16 v[140:143], v[204:207], v[112:115], 0
	ds_read_b128 v[204:207], v174 offset:53248
	v_add_f32_e32 v169, v169, v67
	v_cvt_pk_bf16_f32 v185, v66, v67
	s_waitcnt lgkmcnt(7)
	v_mfma_f32_16x16x32_bf16 v[144:147], v[208:211], v[96:99], 0
	v_add_f32_e32 v222, v222, v68
	v_mfma_f32_16x16x32_bf16 v[148:151], v[208:211], v[112:115], 0
	ds_read_b128 v[208:211], v174 offset:57344
	v_add_f32_e32 v222, v222, v69
	v_cvt_pk_bf16_f32 v186, v72, v73
	s_waitcnt lgkmcnt(7)
	v_mfma_f32_16x16x32_bf16 v[152:155], v[212:215], v[96:99], 0
	v_add_f32_e32 v222, v222, v70
	v_mfma_f32_16x16x32_bf16 v[156:159], v[212:215], v[112:115], 0
	ds_read_b128 v[212:215], v174 offset:61440
	v_add_f32_e32 v222, v222, v71
	v_cvt_pk_bf16_f32 v187, v74, v75
	s_waitcnt lgkmcnt(7)
	v_mfma_f32_16x16x32_bf16 v[128:131], v[230:233], v[100:103], v[128:131]
	v_add_f32_e32 v169, v169, v72
	v_mfma_f32_16x16x32_bf16 v[132:135], v[230:233], v[116:119], v[132:135]
	ds_read_b128 v[230:233], v175 offset:49152
	v_add_f32_e32 v169, v169, v73
	v_cvt_pk_bf16_f32 v188, v80, v81
	s_waitcnt lgkmcnt(7)
	v_mfma_f32_16x16x32_bf16 v[136:139], v[234:237], v[100:103], v[136:139]
	v_add_f32_e32 v169, v169, v74
	v_mfma_f32_16x16x32_bf16 v[140:143], v[234:237], v[116:119], v[140:143]
	ds_read_b128 v[234:237], v175 offset:53248
	v_add_f32_e32 v169, v169, v75
	v_cvt_pk_bf16_f32 v189, v82, v83
	s_waitcnt lgkmcnt(7)
	v_mfma_f32_16x16x32_bf16 v[144:147], v[238:241], v[100:103], v[144:147]
	v_add_f32_e32 v222, v222, v76
	v_mfma_f32_16x16x32_bf16 v[148:151], v[238:241], v[116:119], v[148:151]
	ds_read_b128 v[238:241], v175 offset:57344
	v_add_f32_e32 v222, v222, v77
	v_cvt_pk_bf16_f32 v190, v88, v89
	s_waitcnt lgkmcnt(7)
	v_mfma_f32_16x16x32_bf16 v[152:155], v[242:245], v[100:103], v[152:155]
	v_add_f32_e32 v222, v222, v78
	v_mfma_f32_16x16x32_bf16 v[156:159], v[242:245], v[116:119], v[156:159]
	ds_read_b128 v[242:245], v175 offset:61440
	v_add_f32_e32 v222, v222, v79
	v_cvt_pk_bf16_f32 v191, v90, v91
	s_waitcnt lgkmcnt(7)
	v_mfma_f32_16x16x32_bf16 v[128:131], v[200:203], v[104:107], v[128:131]
	v_add_f32_e32 v169, v169, v80
	s_add_i32 m0, s32, 0x8000
	s_nop 0
	global_load_lds_dwordx4 v183, s[98:99]
	v_mfma_f32_16x16x32_bf16 v[132:135], v[200:203], v[120:123], v[132:135]
	v_add_f32_e32 v169, v169, v81
	v_cvt_pk_bf16_f32 v192, v68, v69
	s_waitcnt lgkmcnt(6)
	v_mfma_f32_16x16x32_bf16 v[136:139], v[204:207], v[104:107], v[136:139]
	v_add_f32_e32 v169, v169, v82
	s_add_i32 m0, s32, 0xa000
	s_nop 0
	global_load_lds_dwordx4 v183, s[100:101]
	s_add_u32 s98, s98, 0x150000
	s_addc_u32 s99, s99, 0
	s_add_u32 s100, s100, 0x150000
	s_addc_u32 s101, s101, 0
	v_mfma_f32_16x16x32_bf16 v[140:143], v[204:207], v[120:123], v[140:143]
	v_add_f32_e32 v169, v169, v83
	v_cvt_pk_bf16_f32 v193, v70, v71
	s_waitcnt lgkmcnt(5)
	v_mfma_f32_16x16x32_bf16 v[144:147], v[208:211], v[104:107], v[144:147]
	v_add_f32_e32 v222, v222, v84
	s_add_i32 m0, s32, 0x10000
	s_nop 0
	global_load_lds_dwordx4 v181, s[0:1]
	v_mfma_f32_16x16x32_bf16 v[148:151], v[208:211], v[120:123], v[148:151]
	v_add_f32_e32 v222, v222, v85
	v_cvt_pk_bf16_f32 v194, v76, v77
	s_add_i32 m0, s32, 0x12000
	s_nop 0
	global_load_lds_dwordx4 v181, s[4:5]
	s_add_u32 s0, s0, 0x150000
	s_addc_u32 s1, s1, 0
	s_add_u32 s4, s4, 0x150000
	s_addc_u32 s5, s5, 0
	s_waitcnt lgkmcnt(4)
	v_mfma_f32_16x16x32_bf16 v[152:155], v[212:215], v[104:107], v[152:155]
	ds_read_b64_tr_b16 v[200:201], v176 offset:32768
	ds_read_b64_tr_b16 v[202:203], v176 offset:36864
	v_add_f32_e32 v222, v222, v86
	v_mfma_f32_16x16x32_bf16 v[156:159], v[212:215], v[120:123], v[156:159]
	v_add_f32_e32 v222, v222, v87
	v_cvt_pk_bf16_f32 v195, v78, v79
	s_waitcnt lgkmcnt(5)
	v_mfma_f32_16x16x32_bf16 v[128:131], v[230:233], v[108:111], v[128:131]
	ds_read_b64_tr_b16 v[204:205], v177 offset:32768
	ds_read_b64_tr_b16 v[206:207], v177 offset:36864
	v_add_f32_e32 v169, v169, v88
	v_mfma_f32_16x16x32_bf16 v[132:135], v[230:233], v[124:127], v[132:135]
	v_add_f32_e32 v169, v169, v89
	v_cvt_pk_bf16_f32 v196, v84, v85
	s_waitcnt lgkmcnt(6)
	v_mfma_f32_16x16x32_bf16 v[136:139], v[234:237], v[108:111], v[136:139]
	ds_read_b64_tr_b16 v[208:209], v178 offset:32768
	ds_read_b64_tr_b16 v[210:211], v178 offset:36864
	v_add_f32_e32 v169, v169, v90
	v_mfma_f32_16x16x32_bf16 v[140:143], v[234:237], v[124:127], v[140:143]
	v_add_f32_e32 v169, v169, v91
	v_cvt_pk_bf16_f32 v197, v86, v87
	s_waitcnt lgkmcnt(7)
	v_mfma_f32_16x16x32_bf16 v[144:147], v[238:241], v[108:111], v[144:147]
	ds_read_b64_tr_b16 v[212:213], v179 offset:32768
	ds_read_b64_tr_b16 v[214:215], v179 offset:36864
	v_add_f32_e32 v222, v222, v92
	v_mfma_f32_16x16x32_bf16 v[148:151], v[238:241], v[124:127], v[148:151]
	v_add_f32_e32 v222, v222, v93
	v_cvt_pk_bf16_f32 v198, v92, v93
	s_waitcnt lgkmcnt(8)
	v_mfma_f32_16x16x32_bf16 v[152:155], v[242:245], v[108:111], v[152:155]
	ds_read_b64_tr_b16 v[230:231], v180 offset:32768
	ds_read_b64_tr_b16 v[232:233], v180 offset:36864
	v_add_f32_e32 v222, v222, v94
	v_mfma_f32_16x16x32_bf16 v[156:159], v[242:245], v[124:127], v[156:159]
	v_add_f32_e32 v222, v222, v95
	v_cvt_pk_bf16_f32 v199, v94, v95
	s_waitcnt lgkmcnt(8)
; __device__ __forceinline__ void partialSM(f32x16& p0, f32x16& p1, float& m_reg, float& mn, float& alpha) {
;     ...
;   for (int r = 0; r < 16; ++r) p0[r] = __builtin_amdgcn_exp2f(p0[r]);
; }
; __device__ __forceinline__ void finishSM(f32x16& p0, f32x16& p1, float alpha, float& l_reg, bf16x8& pa0, bf16x8& pa1, bf16x8& pa2, bf16x8& pa3) {
; #pragma unroll
;   for (int r = 0; r < 16; ++r) p1[r] = __builtin_amdgcn_exp2f(p1[r]);
;   float ps = 0;
; #pragma unroll
;   for (int r = 0; r < 16; ++r) ps += p0[r];
; #pragma unroll
;   for (int r = 0; r < 16; ++r) ps += p1[r];
;   { auto rr = __builtin_amdgcn_permlane32_swap(__float_as_uint(ps), __float_as_uint(ps), false, false);
;     ps = __uint_as_float(rr[0]) + __uint_as_float(rr[1]); }
;   l_reg = l_reg * alpha + ps;
;     ...
;   PK4(p0, 0, pa0); PK4(p0, 8, pa1); PK4(p1, 0, pa2); PK4(p1, 8, pa3);
;     ...
; }
; __device__ __forceinline__ void qkt(f32x16& p0, f32x16& p1, const bf16* Ks, const bf16x8* qr, int r32, int hi) {
;   p0 = f32x16{}; p1 = f32x16{};
; #pragma unroll
;   for (int d0 = 0; d0 < 8; ++d0) { int cb = (d0 * 16 + hi * 8) * 2;
;     bf16x8 b0 = *reinterpret_cast<const bf16x8*>((const char*)Ks + KSWZ(r32, cb));
;     bf16x8 b1 = *reinterpret_cast<const bf16x8*>((const char*)Ks + KSWZ(32 + r32, cb));
;     p0 = __builtin_amdgcn_mfma_f32_32x32x16_bf16(b0, qr[d0], p0, 0, 0, 0);
;     p1 = __builtin_amdgcn_mfma_f32_32x32x16_bf16(b1, qr[d0], p1, 0, 0, 0); }
; }
; __device__ __forceinline__ int v_st(int k, int c) { const int kk = (k & ~0xC) | ((k & 4) << 1) | ((k & 8) >> 1); return ((kk >> 3) * 4 + (c >> 5)) * 512 + ((kk & 7) * 32 + (c & 31)) * 2; }
; __device__ __forceinline__ int v_rd_base(int lane) { return ((lane & 3) << 3) | (((lane >> 2) & 3) << 6) | (((lane >> 4) & 1) << 5) | (((lane >> 5) & 1) << 8); }
; template <int OFF> __device__ __forceinline__ s16x4 tr_read(int vb) {
;   s16x4 r; asm volatile("ds_read_b64_tr_b16 %0, %1 offset:%2" : "=&v"(r) : "v"(vb), "i"(OFF) : "memory"); return r;
; }
; template <int D0> __device__ __forceinline__ void pv_one(f32x16& od, int vb, bf16x8 pa0, bf16x8 pa1, bf16x8 pa2, bf16x8 pa3) {
;   const s16x4 l0 = tr_read<v_rd_off(D0, 0, 0)>(vb), h0 = tr_read<v_rd_off(D0, 0, 1)>(vb), l1 = tr_read<v_rd_off(D0, 1, 0)>(vb), h1 = tr_read<v_rd_off(D0, 1, 1)>(vb);
	v_mfma_f32_16x16x32_bf16 v[0:3], v[200:203], v[184:187], v[0:3]
	v_exp_f32_e32 v128, v128
	v_mfma_f32_16x16x32_bf16 v[32:35], v[200:203], v[192:195], v[32:35]
	ds_read_b64_tr_b16 v[234:235], v182 offset:32768
	ds_read_b64_tr_b16 v[236:237], v182 offset:36864
	v_exp_f32_e32 v129, v129
	s_waitcnt lgkmcnt(8)
	v_mfma_f32_16x16x32_bf16 v[4:7], v[204:207], v[184:187], v[4:7]
	v_exp_f32_e32 v130, v130
	v_mfma_f32_16x16x32_bf16 v[36:39], v[204:207], v[192:195], v[36:39]
	ds_read_b64_tr_b16 v[238:239], v216 offset:32768
	ds_read_b64_tr_b16 v[240:241], v216 offset:36864
	v_exp_f32_e32 v131, v131
	s_waitcnt lgkmcnt(8)
	v_mfma_f32_16x16x32_bf16 v[8:11], v[208:211], v[184:187], v[8:11]
	v_exp_f32_e32 v132, v132
	v_mfma_f32_16x16x32_bf16 v[40:43], v[208:211], v[192:195], v[40:43]
	ds_read_b64_tr_b16 v[242:243], v217 offset:32768
	ds_read_b64_tr_b16 v[244:245], v217 offset:36864
	v_exp_f32_e32 v133, v133
	s_waitcnt lgkmcnt(8)
	v_mfma_f32_16x16x32_bf16 v[12:15], v[212:215], v[184:187], v[12:15]
	v_exp_f32_e32 v134, v134
	v_mfma_f32_16x16x32_bf16 v[44:47], v[212:215], v[192:195], v[44:47]
	ds_read_b64_tr_b16 v[200:201], v176 offset:40960
	ds_read_b64_tr_b16 v[202:203], v176 offset:45056
	v_exp_f32_e32 v135, v135
	s_waitcnt lgkmcnt(8)
	v_mfma_f32_16x16x32_bf16 v[16:19], v[230:233], v[184:187], v[16:19]
	v_exp_f32_e32 v136, v136
	v_mfma_f32_16x16x32_bf16 v[48:51], v[230:233], v[192:195], v[48:51]
	ds_read_b64_tr_b16 v[204:205], v177 offset:40960
	ds_read_b64_tr_b16 v[206:207], v177 offset:45056
	v_exp_f32_e32 v137, v137
	s_waitcnt lgkmcnt(8)
	v_mfma_f32_16x16x32_bf16 v[20:23], v[234:237], v[184:187], v[20:23]
	v_exp_f32_e32 v138, v138
	v_mfma_f32_16x16x32_bf16 v[52:55], v[234:237], v[192:195], v[52:55]
	ds_read_b64_tr_b16 v[208:209], v178 offset:40960
	ds_read_b64_tr_b16 v[210:211], v178 offset:45056
	v_exp_f32_e32 v139, v139
	s_waitcnt lgkmcnt(8)
	v_mfma_f32_16x16x32_bf16 v[24:27], v[238:241], v[184:187], v[24:27]
	v_exp_f32_e32 v140, v140
	v_mfma_f32_16x16x32_bf16 v[56:59], v[238:241], v[192:195], v[56:59]
	ds_read_b64_tr_b16 v[212:213], v179 offset:40960
	ds_read_b64_tr_b16 v[214:215], v179 offset:45056
	v_exp_f32_e32 v141, v141
	s_waitcnt lgkmcnt(8)
	v_mfma_f32_16x16x32_bf16 v[28:31], v[242:245], v[184:187], v[28:31]
	v_exp_f32_e32 v142, v142
	v_mfma_f32_16x16x32_bf16 v[60:63], v[242:245], v[192:195], v[60:63]
	ds_read_b64_tr_b16 v[230:231], v180 offset:40960
	ds_read_b64_tr_b16 v[232:233], v180 offset:45056
	v_exp_f32_e32 v143, v143
	s_waitcnt lgkmcnt(8)
	v_mfma_f32_16x16x32_bf16 v[0:3], v[200:203], v[188:191], v[0:3]
	v_exp_f32_e32 v144, v144
	v_mfma_f32_16x16x32_bf16 v[32:35], v[200:203], v[196:199], v[32:35]
	ds_read_b64_tr_b16 v[234:235], v182 offset:40960
	ds_read_b64_tr_b16 v[236:237], v182 offset:45056
	ds_read_b128 v[200:203], v172 offset:0
	v_exp_f32_e32 v145, v145
	s_waitcnt lgkmcnt(9)
	v_mfma_f32_16x16x32_bf16 v[4:7], v[204:207], v[188:191], v[4:7]
	v_exp_f32_e32 v146, v146
	v_mfma_f32_16x16x32_bf16 v[36:39], v[204:207], v[196:199], v[36:39]
	ds_read_b64_tr_b16 v[238:239], v216 offset:40960
	ds_read_b64_tr_b16 v[240:241], v216 offset:45056
	ds_read_b128 v[204:207], v172 offset:4096
	v_exp_f32_e32 v147, v147
	s_waitcnt lgkmcnt(10)
	v_mfma_f32_16x16x32_bf16 v[8:11], v[208:211], v[188:191], v[8:11]
	v_exp_f32_e32 v148, v148
	v_mfma_f32_16x16x32_bf16 v[40:43], v[208:211], v[196:199], v[40:43]
	ds_read_b64_tr_b16 v[242:243], v217 offset:40960
	ds_read_b64_tr_b16 v[244:245], v217 offset:45056
	ds_read_b128 v[208:211], v172 offset:8192
	v_exp_f32_e32 v149, v149
	s_waitcnt lgkmcnt(11)
	v_mfma_f32_16x16x32_bf16 v[12:15], v[212:215], v[188:191], v[12:15]
	v_exp_f32_e32 v150, v150
	v_mfma_f32_16x16x32_bf16 v[44:47], v[212:215], v[196:199], v[44:47]
	ds_read_b128 v[212:215], v172 offset:12288
	v_exp_f32_e32 v151, v151
	s_waitcnt lgkmcnt(10)
	v_mfma_f32_16x16x32_bf16 v[16:19], v[230:233], v[188:191], v[16:19]
	v_exp_f32_e32 v152, v152
	v_mfma_f32_16x16x32_bf16 v[48:51], v[230:233], v[196:199], v[48:51]
	ds_read_b128 v[230:233], v173 offset:0
	v_exp_f32_e32 v153, v153
	s_waitcnt lgkmcnt(9)
	v_mfma_f32_16x16x32_bf16 v[20:23], v[234:237], v[188:191], v[20:23]
	v_exp_f32_e32 v154, v154
	v_mfma_f32_16x16x32_bf16 v[52:55], v[234:237], v[196:199], v[52:55]
	ds_read_b128 v[234:237], v173 offset:4096
	v_exp_f32_e32 v155, v155
	s_waitcnt lgkmcnt(7)
	v_mfma_f32_16x16x32_bf16 v[24:27], v[238:241], v[188:191], v[24:27]
	v_exp_f32_e32 v156, v156
	v_mfma_f32_16x16x32_bf16 v[56:59], v[238:241], v[196:199], v[56:59]
	ds_read_b128 v[238:241], v173 offset:8192
	v_exp_f32_e32 v157, v157
	s_waitcnt lgkmcnt(5)
	v_mfma_f32_16x16x32_bf16 v[28:31], v[242:245], v[188:191], v[28:31]
	v_exp_f32_e32 v158, v158
	v_mfma_f32_16x16x32_bf16 v[60:63], v[242:245], v[196:199], v[60:63]
	ds_read_b128 v[242:245], v173 offset:12288
	v_exp_f32_e32 v159, v159
	s_waitcnt vmcnt(4)
	s_barrier
; __device__ __forceinline__ void finishSM(f32x16& p0, f32x16& p1, float alpha, float& l_reg, bf16x8& pa0, bf16x8& pa1, bf16x8& pa2, bf16x8& pa3) {
;     ...
;   float ps = 0;
; #pragma unroll
;   for (int r = 0; r < 16; ++r) ps += p0[r];
; #pragma unroll
;   for (int r = 0; r < 16; ++r) ps += p1[r];
;   { auto rr = __builtin_amdgcn_permlane32_swap(__float_as_uint(ps), __float_as_uint(ps), false, false);
;     ps = __uint_as_float(rr[0]) + __uint_as_float(rr[1]); }
;   l_reg = l_reg * alpha + ps;
;     ...
;   PK4(p0, 0, pa0); PK4(p0, 8, pa1); PK4(p1, 0, pa2); PK4(p1, 8, pa3);
;     ...
; }
; __device__ __forceinline__ void qkt(f32x16& p0, f32x16& p1, const bf16* Ks, const bf16x8* qr, int r32, int hi) {
;   p0 = f32x16{}; p1 = f32x16{};
; #pragma unroll
;   for (int d0 = 0; d0 < 8; ++d0) { int cb = (d0 * 16 + hi * 8) * 2;
;     bf16x8 b0 = *reinterpret_cast<const bf16x8*>((const char*)Ks + KSWZ(r32, cb));
;     bf16x8 b1 = *reinterpret_cast<const bf16x8*>((const char*)Ks + KSWZ(32 + r32, cb));
;     p0 = __builtin_amdgcn_mfma_f32_32x32x16_bf16(b0, qr[d0], p0, 0, 0, 0);
;     p1 = __builtin_amdgcn_mfma_f32_32x32x16_bf16(b1, qr[d0], p1, 0, 0, 0); }
; }
	v_mfma_f32_16x16x32_bf16 v[64:67], v[200:203], v[96:99], 0
	v_add_f32_e32 v169, v169, v128
	v_mfma_f32_16x16x32_bf16 v[68:71], v[200:203], v[112:115], 0
	ds_read_b128 v[200:203], v174 offset:0
	v_add_f32_e32 v169, v169, v129
	v_cvt_pk_bf16_f32 v184, v128, v129
	v_mfma_f32_16x16x32_bf16 v[72:75], v[204:207], v[96:99], 0
	v_add_f32_e32 v169, v169, v130
	v_mfma_f32_16x16x32_bf16 v[76:79], v[204:207], v[112:115], 0
	ds_read_b128 v[204:207], v174 offset:4096
	v_add_f32_e32 v169, v169, v131
	v_cvt_pk_bf16_f32 v185, v130, v131
	s_waitcnt lgkmcnt(7)
	v_mfma_f32_16x16x32_bf16 v[80:83], v[208:211], v[96:99], 0
	v_add_f32_e32 v222, v222, v132
	v_mfma_f32_16x16x32_bf16 v[84:87], v[208:211], v[112:115], 0
	ds_read_b128 v[208:211], v174 offset:8192
	v_add_f32_e32 v222, v222, v133
	v_cvt_pk_bf16_f32 v186, v136, v137
	s_waitcnt lgkmcnt(7)
	v_mfma_f32_16x16x32_bf16 v[88:91], v[212:215], v[96:99], 0
	v_add_f32_e32 v222, v222, v134
	v_mfma_f32_16x16x32_bf16 v[92:95], v[212:215], v[112:115], 0
	ds_read_b128 v[212:215], v174 offset:12288
	v_add_f32_e32 v222, v222, v135
	v_cvt_pk_bf16_f32 v187, v138, v139
	s_waitcnt lgkmcnt(7)
	v_mfma_f32_16x16x32_bf16 v[64:67], v[230:233], v[100:103], v[64:67]
	v_add_f32_e32 v169, v169, v136
	v_mfma_f32_16x16x32_bf16 v[68:71], v[230:233], v[116:119], v[68:71]
	ds_read_b128 v[230:233], v175 offset:0
	v_add_f32_e32 v169, v169, v137
	v_cvt_pk_bf16_f32 v188, v144, v145
	s_waitcnt lgkmcnt(7)
	v_mfma_f32_16x16x32_bf16 v[72:75], v[234:237], v[100:103], v[72:75]
	v_add_f32_e32 v169, v169, v138
	v_mfma_f32_16x16x32_bf16 v[76:79], v[234:237], v[116:119], v[76:79]
	ds_read_b128 v[234:237], v175 offset:4096
	v_add_f32_e32 v169, v169, v139
	v_cvt_pk_bf16_f32 v189, v146, v147
	s_waitcnt lgkmcnt(7)
	v_mfma_f32_16x16x32_bf16 v[80:83], v[238:241], v[100:103], v[80:83]
	v_add_f32_e32 v222, v222, v140
	v_mfma_f32_16x16x32_bf16 v[84:87], v[238:241], v[116:119], v[84:87]
	ds_read_b128 v[238:241], v175 offset:8192
	v_add_f32_e32 v222, v222, v141
	v_cvt_pk_bf16_f32 v190, v152, v153
	s_waitcnt lgkmcnt(7)
	v_mfma_f32_16x16x32_bf16 v[88:91], v[242:245], v[100:103], v[88:91]
	v_add_f32_e32 v222, v222, v142
	v_mfma_f32_16x16x32_bf16 v[92:95], v[242:245], v[116:119], v[92:95]
	ds_read_b128 v[242:245], v175 offset:12288
	v_add_f32_e32 v222, v222, v143
	v_cvt_pk_bf16_f32 v191, v154, v155
	s_waitcnt lgkmcnt(7)
	v_mfma_f32_16x16x32_bf16 v[64:67], v[200:203], v[104:107], v[64:67]
	v_add_f32_e32 v169, v169, v144
	s_add_i32 m0, s32, 0xc000
	s_nop 0
	global_load_lds_dwordx4 v183, s[98:99]
	v_mfma_f32_16x16x32_bf16 v[68:71], v[200:203], v[120:123], v[68:71]
	v_add_f32_e32 v169, v169, v145
	v_cvt_pk_bf16_f32 v192, v132, v133
	s_waitcnt lgkmcnt(6)
	v_mfma_f32_16x16x32_bf16 v[72:75], v[204:207], v[104:107], v[72:75]
	v_add_f32_e32 v169, v169, v146
	s_add_i32 m0, s32, 0xe000
	s_nop 0
	global_load_lds_dwordx4 v183, s[100:101]
	s_add_u32 s98, s98, 0x150000
	s_addc_u32 s99, s99, 0
	s_add_u32 s100, s100, 0x150000
	s_addc_u32 s101, s101, 0
	v_mfma_f32_16x16x32_bf16 v[76:79], v[204:207], v[120:123], v[76:79]
	v_add_f32_e32 v169, v169, v147
	v_cvt_pk_bf16_f32 v193, v134, v135
	s_waitcnt lgkmcnt(5)
	v_mfma_f32_16x16x32_bf16 v[80:83], v[208:211], v[104:107], v[80:83]
	v_add_f32_e32 v222, v222, v148
	s_add_i32 m0, s32, 0x14000
	s_nop 0
	global_load_lds_dwordx4 v181, s[0:1]
	v_mfma_f32_16x16x32_bf16 v[84:87], v[208:211], v[120:123], v[84:87]
	v_add_f32_e32 v222, v222, v149
	v_cvt_pk_bf16_f32 v194, v140, v141
	s_add_i32 m0, s32, 0x16000
	s_nop 0
	global_load_lds_dwordx4 v181, s[4:5]
	s_add_u32 s0, s0, 0x150000
	s_addc_u32 s1, s1, 0
	s_add_u32 s4, s4, 0x150000
	s_addc_u32 s5, s5, 0
	s_waitcnt lgkmcnt(4)
	v_mfma_f32_16x16x32_bf16 v[88:91], v[212:215], v[104:107], v[88:91]
	ds_read_b64_tr_b16 v[200:201], v176 offset:49152
	ds_read_b64_tr_b16 v[202:203], v176 offset:53248
	v_add_f32_e32 v222, v222, v150
	v_mfma_f32_16x16x32_bf16 v[92:95], v[212:215], v[120:123], v[92:95]
	v_add_f32_e32 v222, v222, v151
	v_cvt_pk_bf16_f32 v195, v142, v143
	s_waitcnt lgkmcnt(5)
	v_mfma_f32_16x16x32_bf16 v[64:67], v[230:233], v[108:111], v[64:67]
	ds_read_b64_tr_b16 v[204:205], v177 offset:49152
	ds_read_b64_tr_b16 v[206:207], v177 offset:53248
	v_add_f32_e32 v169, v169, v152
	v_mfma_f32_16x16x32_bf16 v[68:71], v[230:233], v[124:127], v[68:71]
	v_add_f32_e32 v169, v169, v153
	v_cvt_pk_bf16_f32 v196, v148, v149
	s_waitcnt lgkmcnt(6)
	v_mfma_f32_16x16x32_bf16 v[72:75], v[234:237], v[108:111], v[72:75]
	ds_read_b64_tr_b16 v[208:209], v178 offset:49152
	ds_read_b64_tr_b16 v[210:211], v178 offset:53248
	v_add_f32_e32 v169, v169, v154
	v_mfma_f32_16x16x32_bf16 v[76:79], v[234:237], v[124:127], v[76:79]
	v_add_f32_e32 v169, v169, v155
	v_cvt_pk_bf16_f32 v197, v150, v151
	s_waitcnt lgkmcnt(7)
	v_mfma_f32_16x16x32_bf16 v[80:83], v[238:241], v[108:111], v[80:83]
	ds_read_b64_tr_b16 v[212:213], v179 offset:49152
	ds_read_b64_tr_b16 v[214:215], v179 offset:53248
	v_add_f32_e32 v222, v222, v156
	v_mfma_f32_16x16x32_bf16 v[84:87], v[238:241], v[124:127], v[84:87]
	v_add_f32_e32 v222, v222, v157
	v_cvt_pk_bf16_f32 v198, v156, v157
	s_waitcnt lgkmcnt(8)
	v_mfma_f32_16x16x32_bf16 v[88:91], v[242:245], v[108:111], v[88:91]
	ds_read_b64_tr_b16 v[230:231], v180 offset:49152
	ds_read_b64_tr_b16 v[232:233], v180 offset:53248
	v_add_f32_e32 v222, v222, v158
	v_mfma_f32_16x16x32_bf16 v[92:95], v[242:245], v[124:127], v[92:95]
	v_add_f32_e32 v222, v222, v159
	v_cvt_pk_bf16_f32 v199, v158, v159
	s_waitcnt lgkmcnt(8)
	v_mfma_f32_16x16x32_bf16 v[0:3], v[200:203], v[184:187], v[0:3]
	v_exp_f32_e32 v64, v64
	v_mfma_f32_16x16x32_bf16 v[32:35], v[200:203], v[192:195], v[32:35]
	ds_read_b64_tr_b16 v[234:235], v182 offset:49152
	ds_read_b64_tr_b16 v[236:237], v182 offset:53248
	v_exp_f32_e32 v65, v65
	s_waitcnt lgkmcnt(8)
; __device__ __forceinline__ void partialSM(f32x16& p0, f32x16& p1, float& m_reg, float& mn, float& alpha) {
;     ...
;   for (int r = 0; r < 16; ++r) p0[r] = __builtin_amdgcn_exp2f(p0[r]);
; }
; __device__ __forceinline__ void finishSM(f32x16& p0, f32x16& p1, float alpha, float& l_reg, bf16x8& pa0, bf16x8& pa1, bf16x8& pa2, bf16x8& pa3) {
; #pragma unroll
;   for (int r = 0; r < 16; ++r) p1[r] = __builtin_amdgcn_exp2f(p1[r]);
;   float ps = 0;
; #pragma unroll
;   for (int r = 0; r < 16; ++r) ps += p0[r];
; #pragma unroll
;   for (int r = 0; r < 16; ++r) ps += p1[r];
;   { auto rr = __builtin_amdgcn_permlane32_swap(__float_as_uint(ps), __float_as_uint(ps), false, false);
;     ps = __uint_as_float(rr[0]) + __uint_as_float(rr[1]); }
;   l_reg = l_reg * alpha + ps;
;     ...
;   PK4(p0, 0, pa0); PK4(p0, 8, pa1); PK4(p1, 0, pa2); PK4(p1, 8, pa3);
;     ...
; }
; __device__ __forceinline__ void qkt(f32x16& p0, f32x16& p1, const bf16* Ks, const bf16x8* qr, int r32, int hi) {
;   p0 = f32x16{}; p1 = f32x16{};
; #pragma unroll
;   for (int d0 = 0; d0 < 8; ++d0) { int cb = (d0 * 16 + hi * 8) * 2;
;     bf16x8 b0 = *reinterpret_cast<const bf16x8*>((const char*)Ks + KSWZ(r32, cb));
;     bf16x8 b1 = *reinterpret_cast<const bf16x8*>((const char*)Ks + KSWZ(32 + r32, cb));
;     p0 = __builtin_amdgcn_mfma_f32_32x32x16_bf16(b0, qr[d0], p0, 0, 0, 0);
;     p1 = __builtin_amdgcn_mfma_f32_32x32x16_bf16(b1, qr[d0], p1, 0, 0, 0); }
; }
; __device__ __forceinline__ int v_st(int k, int c) { const int kk = (k & ~0xC) | ((k & 4) << 1) | ((k & 8) >> 1); return ((kk >> 3) * 4 + (c >> 5)) * 512 + ((kk & 7) * 32 + (c & 31)) * 2; }
; __device__ __forceinline__ int v_rd_base(int lane) { return ((lane & 3) << 3) | (((lane >> 2) & 3) << 6) | (((lane >> 4) & 1) << 5) | (((lane >> 5) & 1) << 8); }
; template <int OFF> __device__ __forceinline__ s16x4 tr_read(int vb) {
;   s16x4 r; asm volatile("ds_read_b64_tr_b16 %0, %1 offset:%2" : "=&v"(r) : "v"(vb), "i"(OFF) : "memory"); return r;
; }
; template <int D0> __device__ __forceinline__ void pv_one(f32x16& od, int vb, bf16x8 pa0, bf16x8 pa1, bf16x8 pa2, bf16x8 pa3) {
;   const s16x4 l0 = tr_read<v_rd_off(D0, 0, 0)>(vb), h0 = tr_read<v_rd_off(D0, 0, 1)>(vb), l1 = tr_read<v_rd_off(D0, 1, 0)>(vb), h1 = tr_read<v_rd_off(D0, 1, 1)>(vb);
	v_mfma_f32_16x16x32_bf16 v[4:7], v[204:207], v[184:187], v[4:7]
	v_exp_f32_e32 v66, v66
	v_mfma_f32_16x16x32_bf16 v[36:39], v[204:207], v[192:195], v[36:39]
	ds_read_b64_tr_b16 v[238:239], v216 offset:49152
	ds_read_b64_tr_b16 v[240:241], v216 offset:53248
	v_exp_f32_e32 v67, v67
	s_waitcnt lgkmcnt(8)
	v_mfma_f32_16x16x32_bf16 v[8:11], v[208:211], v[184:187], v[8:11]
	v_exp_f32_e32 v68, v68
	v_mfma_f32_16x16x32_bf16 v[40:43], v[208:211], v[192:195], v[40:43]
	ds_read_b64_tr_b16 v[242:243], v217 offset:49152
	ds_read_b64_tr_b16 v[244:245], v217 offset:53248
	v_exp_f32_e32 v69, v69
	s_waitcnt lgkmcnt(8)
	v_mfma_f32_16x16x32_bf16 v[12:15], v[212:215], v[184:187], v[12:15]
	v_exp_f32_e32 v70, v70
	v_mfma_f32_16x16x32_bf16 v[44:47], v[212:215], v[192:195], v[44:47]
	ds_read_b64_tr_b16 v[200:201], v176 offset:57344
	ds_read_b64_tr_b16 v[202:203], v176 offset:61440
	v_exp_f32_e32 v71, v71
	s_waitcnt lgkmcnt(8)
	v_mfma_f32_16x16x32_bf16 v[16:19], v[230:233], v[184:187], v[16:19]
	v_exp_f32_e32 v72, v72
	v_mfma_f32_16x16x32_bf16 v[48:51], v[230:233], v[192:195], v[48:51]
	ds_read_b64_tr_b16 v[204:205], v177 offset:57344
	ds_read_b64_tr_b16 v[206:207], v177 offset:61440
	v_exp_f32_e32 v73, v73
	s_waitcnt lgkmcnt(8)
	v_mfma_f32_16x16x32_bf16 v[20:23], v[234:237], v[184:187], v[20:23]
	v_exp_f32_e32 v74, v74
	v_mfma_f32_16x16x32_bf16 v[52:55], v[234:237], v[192:195], v[52:55]
	ds_read_b64_tr_b16 v[208:209], v178 offset:57344
	ds_read_b64_tr_b16 v[210:211], v178 offset:61440
	v_exp_f32_e32 v75, v75
	s_waitcnt lgkmcnt(8)
	v_mfma_f32_16x16x32_bf16 v[24:27], v[238:241], v[184:187], v[24:27]
	v_exp_f32_e32 v76, v76
	v_mfma_f32_16x16x32_bf16 v[56:59], v[238:241], v[192:195], v[56:59]
	ds_read_b64_tr_b16 v[212:213], v179 offset:57344
	ds_read_b64_tr_b16 v[214:215], v179 offset:61440
	v_exp_f32_e32 v77, v77
	s_waitcnt lgkmcnt(8)
	v_mfma_f32_16x16x32_bf16 v[28:31], v[242:245], v[184:187], v[28:31]
	v_exp_f32_e32 v78, v78
	v_mfma_f32_16x16x32_bf16 v[60:63], v[242:245], v[192:195], v[60:63]
	ds_read_b64_tr_b16 v[230:231], v180 offset:57344
	ds_read_b64_tr_b16 v[232:233], v180 offset:61440
	v_exp_f32_e32 v79, v79
	s_waitcnt lgkmcnt(8)
	v_mfma_f32_16x16x32_bf16 v[0:3], v[200:203], v[188:191], v[0:3]
	v_exp_f32_e32 v80, v80
	v_mfma_f32_16x16x32_bf16 v[32:35], v[200:203], v[196:199], v[32:35]
	ds_read_b64_tr_b16 v[234:235], v182 offset:57344
	ds_read_b64_tr_b16 v[236:237], v182 offset:61440
	ds_read_b128 v[200:203], v172 offset:16384
	v_exp_f32_e32 v81, v81
	s_waitcnt lgkmcnt(9)
	v_mfma_f32_16x16x32_bf16 v[4:7], v[204:207], v[188:191], v[4:7]
	v_exp_f32_e32 v82, v82
	v_mfma_f32_16x16x32_bf16 v[36:39], v[204:207], v[196:199], v[36:39]
	ds_read_b64_tr_b16 v[238:239], v216 offset:57344
	ds_read_b64_tr_b16 v[240:241], v216 offset:61440
	ds_read_b128 v[204:207], v172 offset:20480
	v_exp_f32_e32 v83, v83
	s_waitcnt lgkmcnt(10)
	v_mfma_f32_16x16x32_bf16 v[8:11], v[208:211], v[188:191], v[8:11]
	v_exp_f32_e32 v84, v84
	v_mfma_f32_16x16x32_bf16 v[40:43], v[208:211], v[196:199], v[40:43]
	ds_read_b64_tr_b16 v[242:243], v217 offset:57344
	ds_read_b64_tr_b16 v[244:245], v217 offset:61440
	ds_read_b128 v[208:211], v172 offset:24576
	v_exp_f32_e32 v85, v85
	s_waitcnt lgkmcnt(11)
	v_mfma_f32_16x16x32_bf16 v[12:15], v[212:215], v[188:191], v[12:15]
	v_exp_f32_e32 v86, v86
	v_mfma_f32_16x16x32_bf16 v[44:47], v[212:215], v[196:199], v[44:47]
	ds_read_b128 v[212:215], v172 offset:28672
	v_exp_f32_e32 v87, v87
	s_waitcnt lgkmcnt(10)
	v_mfma_f32_16x16x32_bf16 v[16:19], v[230:233], v[188:191], v[16:19]
	v_exp_f32_e32 v88, v88
	v_mfma_f32_16x16x32_bf16 v[48:51], v[230:233], v[196:199], v[48:51]
	ds_read_b128 v[230:233], v173 offset:16384
	v_exp_f32_e32 v89, v89
	s_waitcnt lgkmcnt(9)
	v_mfma_f32_16x16x32_bf16 v[20:23], v[234:237], v[188:191], v[20:23]
	v_exp_f32_e32 v90, v90
	v_mfma_f32_16x16x32_bf16 v[52:55], v[234:237], v[196:199], v[52:55]
	ds_read_b128 v[234:237], v173 offset:20480
	v_exp_f32_e32 v91, v91
	s_waitcnt lgkmcnt(7)
	v_mfma_f32_16x16x32_bf16 v[24:27], v[238:241], v[188:191], v[24:27]
	v_exp_f32_e32 v92, v92
	v_mfma_f32_16x16x32_bf16 v[56:59], v[238:241], v[196:199], v[56:59]
	ds_read_b128 v[238:241], v173 offset:24576
	v_exp_f32_e32 v93, v93
	s_waitcnt lgkmcnt(5)
	v_mfma_f32_16x16x32_bf16 v[28:31], v[242:245], v[188:191], v[28:31]
	v_exp_f32_e32 v94, v94
	v_mfma_f32_16x16x32_bf16 v[60:63], v[242:245], v[196:199], v[60:63]
	ds_read_b128 v[242:245], v173 offset:28672
	v_exp_f32_e32 v95, v95
	s_waitcnt vmcnt(4)
	s_barrier
	s_add_i32 s44, s44, 1
	s_cmp_lt_u32 s44, 63
	s_cbranch_scc1 .Ldense_loop
; __device__ __forceinline__ void finishSM(f32x16& p0, f32x16& p1, float alpha, float& l_reg, bf16x8& pa0, bf16x8& pa1, bf16x8& pa2, bf16x8& pa3) {
;     ...
;   float ps = 0;
; #pragma unroll
;   for (int r = 0; r < 16; ++r) ps += p0[r];
; #pragma unroll
;   for (int r = 0; r < 16; ++r) ps += p1[r];
;   { auto rr = __builtin_amdgcn_permlane32_swap(__float_as_uint(ps), __float_as_uint(ps), false, false);
;     ps = __uint_as_float(rr[0]) + __uint_as_float(rr[1]); }
;   l_reg = l_reg * alpha + ps;
;     ...
;   PK4(p0, 0, pa0); PK4(p0, 8, pa1); PK4(p1, 0, pa2); PK4(p1, 8, pa3);
;     ...
; }
; __device__ __forceinline__ void qkt(f32x16& p0, f32x16& p1, const bf16* Ks, const bf16x8* qr, int r32, int hi) {
;   p0 = f32x16{}; p1 = f32x16{};
; #pragma unroll
;   for (int d0 = 0; d0 < 8; ++d0) { int cb = (d0 * 16 + hi * 8) * 2;
;     bf16x8 b0 = *reinterpret_cast<const bf16x8*>((const char*)Ks + KSWZ(r32, cb));
;     bf16x8 b1 = *reinterpret_cast<const bf16x8*>((const char*)Ks + KSWZ(32 + r32, cb));
;     p0 = __builtin_amdgcn_mfma_f32_32x32x16_bf16(b0, qr[d0], p0, 0, 0, 0);
;     p1 = __builtin_amdgcn_mfma_f32_32x32x16_bf16(b1, qr[d0], p1, 0, 0, 0); }
; }
	v_mfma_f32_16x16x32_bf16 v[128:131], v[200:203], v[96:99], 0
	v_add_f32_e32 v169, v169, v64
	v_mfma_f32_16x16x32_bf16 v[132:135], v[200:203], v[112:115], 0
	ds_read_b128 v[200:203], v174 offset:16384
	v_add_f32_e32 v169, v169, v65
	v_cvt_pk_bf16_f32 v184, v64, v65
	v_mfma_f32_16x16x32_bf16 v[136:139], v[204:207], v[96:99], 0
	v_add_f32_e32 v169, v169, v66
	v_mfma_f32_16x16x32_bf16 v[140:143], v[204:207], v[112:115], 0
	ds_read_b128 v[204:207], v174 offset:20480
	v_add_f32_e32 v169, v169, v67
	v_cvt_pk_bf16_f32 v185, v66, v67
	s_waitcnt lgkmcnt(7)
	v_mfma_f32_16x16x32_bf16 v[144:147], v[208:211], v[96:99], 0
	v_add_f32_e32 v222, v222, v68
	v_mfma_f32_16x16x32_bf16 v[148:151], v[208:211], v[112:115], 0
	ds_read_b128 v[208:211], v174 offset:24576
	v_add_f32_e32 v222, v222, v69
	v_cvt_pk_bf16_f32 v186, v72, v73
	s_waitcnt lgkmcnt(7)
	v_mfma_f32_16x16x32_bf16 v[152:155], v[212:215], v[96:99], 0
	v_add_f32_e32 v222, v222, v70
	v_mfma_f32_16x16x32_bf16 v[156:159], v[212:215], v[112:115], 0
	ds_read_b128 v[212:215], v174 offset:28672
	v_add_f32_e32 v222, v222, v71
	v_cvt_pk_bf16_f32 v187, v74, v75
	s_waitcnt lgkmcnt(7)
	v_mfma_f32_16x16x32_bf16 v[128:131], v[230:233], v[100:103], v[128:131]
	v_add_f32_e32 v169, v169, v72
	v_mfma_f32_16x16x32_bf16 v[132:135], v[230:233], v[116:119], v[132:135]
	ds_read_b128 v[230:233], v175 offset:16384
	v_add_f32_e32 v169, v169, v73
	v_cvt_pk_bf16_f32 v188, v80, v81
	s_waitcnt lgkmcnt(7)
	v_mfma_f32_16x16x32_bf16 v[136:139], v[234:237], v[100:103], v[136:139]
	v_add_f32_e32 v169, v169, v74
	v_mfma_f32_16x16x32_bf16 v[140:143], v[234:237], v[116:119], v[140:143]
	ds_read_b128 v[234:237], v175 offset:20480
	v_add_f32_e32 v169, v169, v75
	v_cvt_pk_bf16_f32 v189, v82, v83
	s_waitcnt lgkmcnt(7)
	v_mfma_f32_16x16x32_bf16 v[144:147], v[238:241], v[100:103], v[144:147]
	v_add_f32_e32 v222, v222, v76
	v_mfma_f32_16x16x32_bf16 v[148:151], v[238:241], v[116:119], v[148:151]
	ds_read_b128 v[238:241], v175 offset:24576
	v_add_f32_e32 v222, v222, v77
	v_cvt_pk_bf16_f32 v190, v88, v89
	s_waitcnt lgkmcnt(7)
	v_mfma_f32_16x16x32_bf16 v[152:155], v[242:245], v[100:103], v[152:155]
	v_add_f32_e32 v222, v222, v78
	v_mfma_f32_16x16x32_bf16 v[156:159], v[242:245], v[116:119], v[156:159]
	ds_read_b128 v[242:245], v175 offset:28672
	v_add_f32_e32 v222, v222, v79
	v_cvt_pk_bf16_f32 v191, v90, v91
	s_waitcnt lgkmcnt(7)
	v_mfma_f32_16x16x32_bf16 v[128:131], v[200:203], v[104:107], v[128:131]
	v_add_f32_e32 v169, v169, v80
	s_add_i32 m0, s32, 0x18000
	s_nop 0
	global_load_lds_dwordx4 v181, s[0:1]
	v_mfma_f32_16x16x32_bf16 v[132:135], v[200:203], v[120:123], v[132:135]
	v_add_f32_e32 v169, v169, v81
	v_cvt_pk_bf16_f32 v192, v68, v69
	s_waitcnt lgkmcnt(6)
	v_mfma_f32_16x16x32_bf16 v[136:139], v[204:207], v[104:107], v[136:139]
	v_add_f32_e32 v169, v169, v82
	s_add_i32 m0, s32, 0x1a000
	s_nop 0
	global_load_lds_dwordx4 v181, s[4:5]
	s_add_u32 s0, s0, 0x150000
	s_addc_u32 s1, s1, 0
	s_add_u32 s4, s4, 0x150000
	s_addc_u32 s5, s5, 0
	v_mfma_f32_16x16x32_bf16 v[140:143], v[204:207], v[120:123], v[140:143]
	v_add_f32_e32 v169, v169, v83
	v_cvt_pk_bf16_f32 v193, v70, v71
	s_waitcnt lgkmcnt(5)
	v_mfma_f32_16x16x32_bf16 v[144:147], v[208:211], v[104:107], v[144:147]
	v_add_f32_e32 v222, v222, v84
	v_mfma_f32_16x16x32_bf16 v[148:151], v[208:211], v[120:123], v[148:151]
	v_add_f32_e32 v222, v222, v85
	v_cvt_pk_bf16_f32 v194, v76, v77
	s_waitcnt lgkmcnt(4)
	v_mfma_f32_16x16x32_bf16 v[152:155], v[212:215], v[104:107], v[152:155]
	ds_read_b64_tr_b16 v[200:201], v176 offset:0
	ds_read_b64_tr_b16 v[202:203], v176 offset:4096
	v_add_f32_e32 v222, v222, v86
	v_mfma_f32_16x16x32_bf16 v[156:159], v[212:215], v[120:123], v[156:159]
	v_add_f32_e32 v222, v222, v87
	v_cvt_pk_bf16_f32 v195, v78, v79
	s_waitcnt lgkmcnt(5)
	v_mfma_f32_16x16x32_bf16 v[128:131], v[230:233], v[108:111], v[128:131]
	ds_read_b64_tr_b16 v[204:205], v177 offset:0
	ds_read_b64_tr_b16 v[206:207], v177 offset:4096
	v_add_f32_e32 v169, v169, v88
	v_mfma_f32_16x16x32_bf16 v[132:135], v[230:233], v[124:127], v[132:135]
	v_add_f32_e32 v169, v169, v89
	v_cvt_pk_bf16_f32 v196, v84, v85
	s_waitcnt lgkmcnt(6)
	v_mfma_f32_16x16x32_bf16 v[136:139], v[234:237], v[108:111], v[136:139]
	ds_read_b64_tr_b16 v[208:209], v178 offset:0
	ds_read_b64_tr_b16 v[210:211], v178 offset:4096
	v_add_f32_e32 v169, v169, v90
	v_mfma_f32_16x16x32_bf16 v[140:143], v[234:237], v[124:127], v[140:143]
	v_add_f32_e32 v169, v169, v91
	v_cvt_pk_bf16_f32 v197, v86, v87
	s_waitcnt lgkmcnt(7)
	v_mfma_f32_16x16x32_bf16 v[144:147], v[238:241], v[108:111], v[144:147]
	ds_read_b64_tr_b16 v[212:213], v179 offset:0
	ds_read_b64_tr_b16 v[214:215], v179 offset:4096
	v_add_f32_e32 v222, v222, v92
	v_mfma_f32_16x16x32_bf16 v[148:151], v[238:241], v[124:127], v[148:151]
	v_add_f32_e32 v222, v222, v93
	v_cvt_pk_bf16_f32 v198, v92, v93
	s_waitcnt lgkmcnt(8)
	v_mfma_f32_16x16x32_bf16 v[152:155], v[242:245], v[108:111], v[152:155]
	ds_read_b64_tr_b16 v[230:231], v180 offset:0
	ds_read_b64_tr_b16 v[232:233], v180 offset:4096
	v_add_f32_e32 v222, v222, v94
	v_mfma_f32_16x16x32_bf16 v[156:159], v[242:245], v[124:127], v[156:159]
	v_add_f32_e32 v222, v222, v95
	v_cvt_pk_bf16_f32 v199, v94, v95
	s_waitcnt lgkmcnt(8)
	v_mfma_f32_16x16x32_bf16 v[0:3], v[200:203], v[184:187], v[0:3]
	v_exp_f32_e32 v128, v128
	v_mfma_f32_16x16x32_bf16 v[32:35], v[200:203], v[192:195], v[32:35]
	ds_read_b64_tr_b16 v[234:235], v182 offset:0
	ds_read_b64_tr_b16 v[236:237], v182 offset:4096
	v_exp_f32_e32 v129, v129
	s_waitcnt lgkmcnt(8)
; __device__ __forceinline__ void partialSM(f32x16& p0, f32x16& p1, float& m_reg, float& mn, float& alpha) {
;     ...
;   for (int r = 0; r < 16; ++r) p0[r] = __builtin_amdgcn_exp2f(p0[r]);
; }
; __device__ __forceinline__ void finishSM(f32x16& p0, f32x16& p1, float alpha, float& l_reg, bf16x8& pa0, bf16x8& pa1, bf16x8& pa2, bf16x8& pa3) {
; #pragma unroll
;   for (int r = 0; r < 16; ++r) p1[r] = __builtin_amdgcn_exp2f(p1[r]);
;   float ps = 0;
; #pragma unroll
;   for (int r = 0; r < 16; ++r) ps += p0[r];
; #pragma unroll
;   for (int r = 0; r < 16; ++r) ps += p1[r];
;   { auto rr = __builtin_amdgcn_permlane32_swap(__float_as_uint(ps), __float_as_uint(ps), false, false);
;     ps = __uint_as_float(rr[0]) + __uint_as_float(rr[1]); }
;   l_reg = l_reg * alpha + ps;
;     ...
;   PK4(p0, 0, pa0); PK4(p0, 8, pa1); PK4(p1, 0, pa2); PK4(p1, 8, pa3);
;     ...
; }
; __device__ __forceinline__ void qkt(f32x16& p0, f32x16& p1, const bf16* Ks, const bf16x8* qr, int r32, int hi) {
;   p0 = f32x16{}; p1 = f32x16{};
; #pragma unroll
;   for (int d0 = 0; d0 < 8; ++d0) { int cb = (d0 * 16 + hi * 8) * 2;
;     bf16x8 b0 = *reinterpret_cast<const bf16x8*>((const char*)Ks + KSWZ(r32, cb));
;     bf16x8 b1 = *reinterpret_cast<const bf16x8*>((const char*)Ks + KSWZ(32 + r32, cb));
;     p0 = __builtin_amdgcn_mfma_f32_32x32x16_bf16(b0, qr[d0], p0, 0, 0, 0);
;     p1 = __builtin_amdgcn_mfma_f32_32x32x16_bf16(b1, qr[d0], p1, 0, 0, 0); }
; }
; __device__ __forceinline__ int v_st(int k, int c) { const int kk = (k & ~0xC) | ((k & 4) << 1) | ((k & 8) >> 1); return ((kk >> 3) * 4 + (c >> 5)) * 512 + ((kk & 7) * 32 + (c & 31)) * 2; }
; __device__ __forceinline__ int v_rd_base(int lane) { return ((lane & 3) << 3) | (((lane >> 2) & 3) << 6) | (((lane >> 4) & 1) << 5) | (((lane >> 5) & 1) << 8); }
; template <int OFF> __device__ __forceinline__ s16x4 tr_read(int vb) {
;   s16x4 r; asm volatile("ds_read_b64_tr_b16 %0, %1 offset:%2" : "=&v"(r) : "v"(vb), "i"(OFF) : "memory"); return r;
; }
; template <int D0> __device__ __forceinline__ void pv_one(f32x16& od, int vb, bf16x8 pa0, bf16x8 pa1, bf16x8 pa2, bf16x8 pa3) {
;   const s16x4 l0 = tr_read<v_rd_off(D0, 0, 0)>(vb), h0 = tr_read<v_rd_off(D0, 0, 1)>(vb), l1 = tr_read<v_rd_off(D0, 1, 0)>(vb), h1 = tr_read<v_rd_off(D0, 1, 1)>(vb);
	v_mfma_f32_16x16x32_bf16 v[4:7], v[204:207], v[184:187], v[4:7]
	v_exp_f32_e32 v130, v130
	v_mfma_f32_16x16x32_bf16 v[36:39], v[204:207], v[192:195], v[36:39]
	ds_read_b64_tr_b16 v[238:239], v216 offset:0
	ds_read_b64_tr_b16 v[240:241], v216 offset:4096
	v_exp_f32_e32 v131, v131
	s_waitcnt lgkmcnt(8)
	v_mfma_f32_16x16x32_bf16 v[8:11], v[208:211], v[184:187], v[8:11]
	v_exp_f32_e32 v132, v132
	v_mfma_f32_16x16x32_bf16 v[40:43], v[208:211], v[192:195], v[40:43]
	ds_read_b64_tr_b16 v[242:243], v217 offset:0
	ds_read_b64_tr_b16 v[244:245], v217 offset:4096
	v_exp_f32_e32 v133, v133
	s_waitcnt lgkmcnt(8)
	v_mfma_f32_16x16x32_bf16 v[12:15], v[212:215], v[184:187], v[12:15]
	v_exp_f32_e32 v134, v134
	v_mfma_f32_16x16x32_bf16 v[44:47], v[212:215], v[192:195], v[44:47]
	ds_read_b64_tr_b16 v[200:201], v176 offset:8192
	ds_read_b64_tr_b16 v[202:203], v176 offset:12288
	v_exp_f32_e32 v135, v135
	s_waitcnt lgkmcnt(8)
	v_mfma_f32_16x16x32_bf16 v[16:19], v[230:233], v[184:187], v[16:19]
	v_exp_f32_e32 v136, v136
	v_mfma_f32_16x16x32_bf16 v[48:51], v[230:233], v[192:195], v[48:51]
	ds_read_b64_tr_b16 v[204:205], v177 offset:8192
	ds_read_b64_tr_b16 v[206:207], v177 offset:12288
	v_exp_f32_e32 v137, v137
	s_waitcnt lgkmcnt(8)
	v_mfma_f32_16x16x32_bf16 v[20:23], v[234:237], v[184:187], v[20:23]
	v_exp_f32_e32 v138, v138
	v_mfma_f32_16x16x32_bf16 v[52:55], v[234:237], v[192:195], v[52:55]
	ds_read_b64_tr_b16 v[208:209], v178 offset:8192
	ds_read_b64_tr_b16 v[210:211], v178 offset:12288
	v_exp_f32_e32 v139, v139
	s_waitcnt lgkmcnt(8)
	v_mfma_f32_16x16x32_bf16 v[24:27], v[238:241], v[184:187], v[24:27]
	v_exp_f32_e32 v140, v140
	v_mfma_f32_16x16x32_bf16 v[56:59], v[238:241], v[192:195], v[56:59]
	ds_read_b64_tr_b16 v[212:213], v179 offset:8192
	ds_read_b64_tr_b16 v[214:215], v179 offset:12288
	v_exp_f32_e32 v141, v141
	s_waitcnt lgkmcnt(8)
	v_mfma_f32_16x16x32_bf16 v[28:31], v[242:245], v[184:187], v[28:31]
	v_exp_f32_e32 v142, v142
	v_mfma_f32_16x16x32_bf16 v[60:63], v[242:245], v[192:195], v[60:63]
	ds_read_b64_tr_b16 v[230:231], v180 offset:8192
	ds_read_b64_tr_b16 v[232:233], v180 offset:12288
	v_exp_f32_e32 v143, v143
	s_waitcnt lgkmcnt(8)
	v_mfma_f32_16x16x32_bf16 v[0:3], v[200:203], v[188:191], v[0:3]
	v_exp_f32_e32 v144, v144
	v_mfma_f32_16x16x32_bf16 v[32:35], v[200:203], v[196:199], v[32:35]
	ds_read_b64_tr_b16 v[234:235], v182 offset:8192
	ds_read_b64_tr_b16 v[236:237], v182 offset:12288
	ds_read_b128 v[200:203], v172 offset:32768
	v_exp_f32_e32 v145, v145
	s_waitcnt lgkmcnt(9)
	v_mfma_f32_16x16x32_bf16 v[4:7], v[204:207], v[188:191], v[4:7]
	v_exp_f32_e32 v146, v146
	v_mfma_f32_16x16x32_bf16 v[36:39], v[204:207], v[196:199], v[36:39]
	ds_read_b64_tr_b16 v[238:239], v216 offset:8192
	ds_read_b64_tr_b16 v[240:241], v216 offset:12288
	ds_read_b128 v[204:207], v172 offset:36864
	v_exp_f32_e32 v147, v147
	s_waitcnt lgkmcnt(10)
	v_mfma_f32_16x16x32_bf16 v[8:11], v[208:211], v[188:191], v[8:11]
	v_exp_f32_e32 v148, v148
	v_mfma_f32_16x16x32_bf16 v[40:43], v[208:211], v[196:199], v[40:43]
	ds_read_b64_tr_b16 v[242:243], v217 offset:8192
	ds_read_b64_tr_b16 v[244:245], v217 offset:12288
	ds_read_b128 v[208:211], v172 offset:40960
	v_exp_f32_e32 v149, v149
	s_waitcnt lgkmcnt(11)
	v_mfma_f32_16x16x32_bf16 v[12:15], v[212:215], v[188:191], v[12:15]
	v_exp_f32_e32 v150, v150
	v_mfma_f32_16x16x32_bf16 v[44:47], v[212:215], v[196:199], v[44:47]
	ds_read_b128 v[212:215], v172 offset:45056
	v_exp_f32_e32 v151, v151
	s_waitcnt lgkmcnt(10)
	v_mfma_f32_16x16x32_bf16 v[16:19], v[230:233], v[188:191], v[16:19]
	v_exp_f32_e32 v152, v152
	v_mfma_f32_16x16x32_bf16 v[48:51], v[230:233], v[196:199], v[48:51]
	ds_read_b128 v[230:233], v173 offset:32768
	v_exp_f32_e32 v153, v153
	s_waitcnt lgkmcnt(9)
	v_mfma_f32_16x16x32_bf16 v[20:23], v[234:237], v[188:191], v[20:23]
	v_exp_f32_e32 v154, v154
	v_mfma_f32_16x16x32_bf16 v[52:55], v[234:237], v[196:199], v[52:55]
	ds_read_b128 v[234:237], v173 offset:36864
	v_exp_f32_e32 v155, v155
	s_waitcnt lgkmcnt(7)
	v_mfma_f32_16x16x32_bf16 v[24:27], v[238:241], v[188:191], v[24:27]
	v_exp_f32_e32 v156, v156
	v_mfma_f32_16x16x32_bf16 v[56:59], v[238:241], v[196:199], v[56:59]
	ds_read_b128 v[238:241], v173 offset:40960
	v_exp_f32_e32 v157, v157
	s_waitcnt lgkmcnt(5)
	v_mfma_f32_16x16x32_bf16 v[28:31], v[242:245], v[188:191], v[28:31]
	v_exp_f32_e32 v158, v158
	v_mfma_f32_16x16x32_bf16 v[60:63], v[242:245], v[196:199], v[60:63]
	ds_read_b128 v[242:245], v173 offset:45056
	v_exp_f32_e32 v159, v159
	s_waitcnt vmcnt(2)
	s_barrier
; __device__ __forceinline__ void finishSM(f32x16& p0, f32x16& p1, float alpha, float& l_reg, bf16x8& pa0, bf16x8& pa1, bf16x8& pa2, bf16x8& pa3) {
;     ...
;   float ps = 0;
; #pragma unroll
;   for (int r = 0; r < 16; ++r) ps += p0[r];
; #pragma unroll
;   for (int r = 0; r < 16; ++r) ps += p1[r];
;   { auto rr = __builtin_amdgcn_permlane32_swap(__float_as_uint(ps), __float_as_uint(ps), false, false);
;     ps = __uint_as_float(rr[0]) + __uint_as_float(rr[1]); }
;   l_reg = l_reg * alpha + ps;
;     ...
;   PK4(p0, 0, pa0); PK4(p0, 8, pa1); PK4(p1, 0, pa2); PK4(p1, 8, pa3);
;     ...
; }
; __device__ __forceinline__ void qkt(f32x16& p0, f32x16& p1, const bf16* Ks, const bf16x8* qr, int r32, int hi) {
;   p0 = f32x16{}; p1 = f32x16{};
; #pragma unroll
;   for (int d0 = 0; d0 < 8; ++d0) { int cb = (d0 * 16 + hi * 8) * 2;
;     bf16x8 b0 = *reinterpret_cast<const bf16x8*>((const char*)Ks + KSWZ(r32, cb));
;     bf16x8 b1 = *reinterpret_cast<const bf16x8*>((const char*)Ks + KSWZ(32 + r32, cb));
;     p0 = __builtin_amdgcn_mfma_f32_32x32x16_bf16(b0, qr[d0], p0, 0, 0, 0);
;     p1 = __builtin_amdgcn_mfma_f32_32x32x16_bf16(b1, qr[d0], p1, 0, 0, 0); }
; }
	v_mfma_f32_16x16x32_bf16 v[64:67], v[200:203], v[96:99], 0
	v_add_f32_e32 v169, v169, v128
	v_mfma_f32_16x16x32_bf16 v[68:71], v[200:203], v[112:115], 0
	ds_read_b128 v[200:203], v174 offset:32768
	v_add_f32_e32 v169, v169, v129
	v_cvt_pk_bf16_f32 v184, v128, v129
	v_mfma_f32_16x16x32_bf16 v[72:75], v[204:207], v[96:99], 0
	v_add_f32_e32 v169, v169, v130
	v_mfma_f32_16x16x32_bf16 v[76:79], v[204:207], v[112:115], 0
	ds_read_b128 v[204:207], v174 offset:36864
	v_add_f32_e32 v169, v169, v131
	v_cvt_pk_bf16_f32 v185, v130, v131
	s_waitcnt lgkmcnt(7)
	v_mfma_f32_16x16x32_bf16 v[80:83], v[208:211], v[96:99], 0
	v_add_f32_e32 v222, v222, v132
	v_mfma_f32_16x16x32_bf16 v[84:87], v[208:211], v[112:115], 0
	ds_read_b128 v[208:211], v174 offset:40960
	v_add_f32_e32 v222, v222, v133
	v_cvt_pk_bf16_f32 v186, v136, v137
	s_waitcnt lgkmcnt(7)
	v_mfma_f32_16x16x32_bf16 v[88:91], v[212:215], v[96:99], 0
	v_add_f32_e32 v222, v222, v134
	v_mfma_f32_16x16x32_bf16 v[92:95], v[212:215], v[112:115], 0
	ds_read_b128 v[212:215], v174 offset:45056
	v_add_f32_e32 v222, v222, v135
	v_cvt_pk_bf16_f32 v187, v138, v139
	s_waitcnt lgkmcnt(7)
	v_mfma_f32_16x16x32_bf16 v[64:67], v[230:233], v[100:103], v[64:67]
	v_add_f32_e32 v169, v169, v136
	v_mfma_f32_16x16x32_bf16 v[68:71], v[230:233], v[116:119], v[68:71]
	ds_read_b128 v[230:233], v175 offset:32768
	v_add_f32_e32 v169, v169, v137
	v_cvt_pk_bf16_f32 v188, v144, v145
	s_waitcnt lgkmcnt(7)
	v_mfma_f32_16x16x32_bf16 v[72:75], v[234:237], v[100:103], v[72:75]
	v_add_f32_e32 v169, v169, v138
	v_mfma_f32_16x16x32_bf16 v[76:79], v[234:237], v[116:119], v[76:79]
	ds_read_b128 v[234:237], v175 offset:36864
	v_add_f32_e32 v169, v169, v139
	v_cvt_pk_bf16_f32 v189, v146, v147
	s_waitcnt lgkmcnt(7)
	v_mfma_f32_16x16x32_bf16 v[80:83], v[238:241], v[100:103], v[80:83]
	v_add_f32_e32 v222, v222, v140
	v_mfma_f32_16x16x32_bf16 v[84:87], v[238:241], v[116:119], v[84:87]
	ds_read_b128 v[238:241], v175 offset:40960
	v_add_f32_e32 v222, v222, v141
	v_cvt_pk_bf16_f32 v190, v152, v153
	s_waitcnt lgkmcnt(7)
	v_mfma_f32_16x16x32_bf16 v[88:91], v[242:245], v[100:103], v[88:91]
	v_add_f32_e32 v222, v222, v142
	v_mfma_f32_16x16x32_bf16 v[92:95], v[242:245], v[116:119], v[92:95]
	ds_read_b128 v[242:245], v175 offset:45056
	v_add_f32_e32 v222, v222, v143
	v_cvt_pk_bf16_f32 v191, v154, v155
	s_waitcnt lgkmcnt(7)
	v_mfma_f32_16x16x32_bf16 v[64:67], v[200:203], v[104:107], v[64:67]
	v_add_f32_e32 v169, v169, v144
	s_add_i32 m0, s32, 0x1c000
	s_nop 0
	global_load_lds_dwordx4 v181, s[0:1]
	v_mfma_f32_16x16x32_bf16 v[68:71], v[200:203], v[120:123], v[68:71]
	v_add_f32_e32 v169, v169, v145
	v_cvt_pk_bf16_f32 v192, v132, v133
	s_waitcnt lgkmcnt(6)
	v_mfma_f32_16x16x32_bf16 v[72:75], v[204:207], v[104:107], v[72:75]
	v_add_f32_e32 v169, v169, v146
	s_add_i32 m0, s32, 0x1e000
	s_nop 0
	global_load_lds_dwordx4 v181, s[4:5]
	s_add_u32 s0, s0, 0x150000
	s_addc_u32 s1, s1, 0
	s_add_u32 s4, s4, 0x150000
	s_addc_u32 s5, s5, 0
	v_mfma_f32_16x16x32_bf16 v[76:79], v[204:207], v[120:123], v[76:79]
	v_add_f32_e32 v169, v169, v147
	v_cvt_pk_bf16_f32 v193, v134, v135
	s_waitcnt lgkmcnt(5)
	v_mfma_f32_16x16x32_bf16 v[80:83], v[208:211], v[104:107], v[80:83]
	v_add_f32_e32 v222, v222, v148
	v_mfma_f32_16x16x32_bf16 v[84:87], v[208:211], v[120:123], v[84:87]
	v_add_f32_e32 v222, v222, v149
	v_cvt_pk_bf16_f32 v194, v140, v141
	s_waitcnt lgkmcnt(4)
	v_mfma_f32_16x16x32_bf16 v[88:91], v[212:215], v[104:107], v[88:91]
	ds_read_b64_tr_b16 v[200:201], v176 offset:16384
	ds_read_b64_tr_b16 v[202:203], v176 offset:20480
	v_add_f32_e32 v222, v222, v150
	v_mfma_f32_16x16x32_bf16 v[92:95], v[212:215], v[120:123], v[92:95]
	v_add_f32_e32 v222, v222, v151
	v_cvt_pk_bf16_f32 v195, v142, v143
	s_waitcnt lgkmcnt(5)
	v_mfma_f32_16x16x32_bf16 v[64:67], v[230:233], v[108:111], v[64:67]
	ds_read_b64_tr_b16 v[204:205], v177 offset:16384
	ds_read_b64_tr_b16 v[206:207], v177 offset:20480
	v_add_f32_e32 v169, v169, v152
	v_mfma_f32_16x16x32_bf16 v[68:71], v[230:233], v[124:127], v[68:71]
	v_add_f32_e32 v169, v169, v153
	v_cvt_pk_bf16_f32 v196, v148, v149
	s_waitcnt lgkmcnt(6)
	v_mfma_f32_16x16x32_bf16 v[72:75], v[234:237], v[108:111], v[72:75]
	ds_read_b64_tr_b16 v[208:209], v178 offset:16384
	ds_read_b64_tr_b16 v[210:211], v178 offset:20480
	v_add_f32_e32 v169, v169, v154
	v_mfma_f32_16x16x32_bf16 v[76:79], v[234:237], v[124:127], v[76:79]
	v_add_f32_e32 v169, v169, v155
	v_cvt_pk_bf16_f32 v197, v150, v151
	s_waitcnt lgkmcnt(7)
	v_mfma_f32_16x16x32_bf16 v[80:83], v[238:241], v[108:111], v[80:83]
	ds_read_b64_tr_b16 v[212:213], v179 offset:16384
	ds_read_b64_tr_b16 v[214:215], v179 offset:20480
	v_add_f32_e32 v222, v222, v156
	v_mfma_f32_16x16x32_bf16 v[84:87], v[238:241], v[124:127], v[84:87]
	v_add_f32_e32 v222, v222, v157
	v_cvt_pk_bf16_f32 v198, v156, v157
	s_waitcnt lgkmcnt(8)
	v_mfma_f32_16x16x32_bf16 v[88:91], v[242:245], v[108:111], v[88:91]
	ds_read_b64_tr_b16 v[230:231], v180 offset:16384
	ds_read_b64_tr_b16 v[232:233], v180 offset:20480
	v_add_f32_e32 v222, v222, v158
	v_mfma_f32_16x16x32_bf16 v[92:95], v[242:245], v[124:127], v[92:95]
	v_add_f32_e32 v222, v222, v159
	v_cvt_pk_bf16_f32 v199, v158, v159
	s_waitcnt lgkmcnt(8)
	v_mfma_f32_16x16x32_bf16 v[0:3], v[200:203], v[184:187], v[0:3]
	v_exp_f32_e32 v64, v64
	v_mfma_f32_16x16x32_bf16 v[32:35], v[200:203], v[192:195], v[32:35]
	ds_read_b64_tr_b16 v[234:235], v182 offset:16384
	ds_read_b64_tr_b16 v[236:237], v182 offset:20480
	v_exp_f32_e32 v65, v65
	s_waitcnt lgkmcnt(8)
	v_mfma_f32_16x16x32_bf16 v[4:7], v[204:207], v[184:187], v[4:7]
	v_exp_f32_e32 v66, v66
	v_mfma_f32_16x16x32_bf16 v[36:39], v[204:207], v[192:195], v[36:39]
	ds_read_b64_tr_b16 v[238:239], v216 offset:16384
	ds_read_b64_tr_b16 v[240:241], v216 offset:20480
	v_exp_f32_e32 v67, v67
	s_waitcnt lgkmcnt(8)
; __device__ __forceinline__ void partialSM(f32x16& p0, f32x16& p1, float& m_reg, float& mn, float& alpha) {
;     ...
;   for (int r = 0; r < 16; ++r) p0[r] = __builtin_amdgcn_exp2f(p0[r]);
; }
; __device__ __forceinline__ void finishSM(f32x16& p0, f32x16& p1, float alpha, float& l_reg, bf16x8& pa0, bf16x8& pa1, bf16x8& pa2, bf16x8& pa3) {
; #pragma unroll
;   for (int r = 0; r < 16; ++r) p1[r] = __builtin_amdgcn_exp2f(p1[r]);
;   float ps = 0;
; #pragma unroll
;   for (int r = 0; r < 16; ++r) ps += p0[r];
; #pragma unroll
;   for (int r = 0; r < 16; ++r) ps += p1[r];
;   { auto rr = __builtin_amdgcn_permlane32_swap(__float_as_uint(ps), __float_as_uint(ps), false, false);
;     ps = __uint_as_float(rr[0]) + __uint_as_float(rr[1]); }
;   l_reg = l_reg * alpha + ps;
;     ...
;   PK4(p0, 0, pa0); PK4(p0, 8, pa1); PK4(p1, 0, pa2); PK4(p1, 8, pa3);
;     ...
; }
; __device__ __forceinline__ void qkt(f32x16& p0, f32x16& p1, const bf16* Ks, const bf16x8* qr, int r32, int hi) {
;   p0 = f32x16{}; p1 = f32x16{};
; #pragma unroll
;   for (int d0 = 0; d0 < 8; ++d0) { int cb = (d0 * 16 + hi * 8) * 2;
;     bf16x8 b0 = *reinterpret_cast<const bf16x8*>((const char*)Ks + KSWZ(r32, cb));
;     bf16x8 b1 = *reinterpret_cast<const bf16x8*>((const char*)Ks + KSWZ(32 + r32, cb));
;     p0 = __builtin_amdgcn_mfma_f32_32x32x16_bf16(b0, qr[d0], p0, 0, 0, 0);
;     p1 = __builtin_amdgcn_mfma_f32_32x32x16_bf16(b1, qr[d0], p1, 0, 0, 0); }
; }
; __device__ __forceinline__ int v_st(int k, int c) { const int kk = (k & ~0xC) | ((k & 4) << 1) | ((k & 8) >> 1); return ((kk >> 3) * 4 + (c >> 5)) * 512 + ((kk & 7) * 32 + (c & 31)) * 2; }
; __device__ __forceinline__ int v_rd_base(int lane) { return ((lane & 3) << 3) | (((lane >> 2) & 3) << 6) | (((lane >> 4) & 1) << 5) | (((lane >> 5) & 1) << 8); }
; template <int OFF> __device__ __forceinline__ s16x4 tr_read(int vb) {
;   s16x4 r; asm volatile("ds_read_b64_tr_b16 %0, %1 offset:%2" : "=&v"(r) : "v"(vb), "i"(OFF) : "memory"); return r;
; }
; template <int D0> __device__ __forceinline__ void pv_one(f32x16& od, int vb, bf16x8 pa0, bf16x8 pa1, bf16x8 pa2, bf16x8 pa3) {
;   const s16x4 l0 = tr_read<v_rd_off(D0, 0, 0)>(vb), h0 = tr_read<v_rd_off(D0, 0, 1)>(vb), l1 = tr_read<v_rd_off(D0, 1, 0)>(vb), h1 = tr_read<v_rd_off(D0, 1, 1)>(vb);
	v_mfma_f32_16x16x32_bf16 v[8:11], v[208:211], v[184:187], v[8:11]
	v_exp_f32_e32 v68, v68
	v_mfma_f32_16x16x32_bf16 v[40:43], v[208:211], v[192:195], v[40:43]
	ds_read_b64_tr_b16 v[242:243], v217 offset:16384
	ds_read_b64_tr_b16 v[244:245], v217 offset:20480
	v_exp_f32_e32 v69, v69
	s_waitcnt lgkmcnt(8)
	v_mfma_f32_16x16x32_bf16 v[12:15], v[212:215], v[184:187], v[12:15]
	v_exp_f32_e32 v70, v70
	v_mfma_f32_16x16x32_bf16 v[44:47], v[212:215], v[192:195], v[44:47]
	ds_read_b64_tr_b16 v[200:201], v176 offset:24576
	ds_read_b64_tr_b16 v[202:203], v176 offset:28672
	v_exp_f32_e32 v71, v71
	s_waitcnt lgkmcnt(8)
	v_mfma_f32_16x16x32_bf16 v[16:19], v[230:233], v[184:187], v[16:19]
	v_exp_f32_e32 v72, v72
	v_mfma_f32_16x16x32_bf16 v[48:51], v[230:233], v[192:195], v[48:51]
	ds_read_b64_tr_b16 v[204:205], v177 offset:24576
	ds_read_b64_tr_b16 v[206:207], v177 offset:28672
	v_exp_f32_e32 v73, v73
	s_waitcnt lgkmcnt(8)
	v_mfma_f32_16x16x32_bf16 v[20:23], v[234:237], v[184:187], v[20:23]
	v_exp_f32_e32 v74, v74
	v_mfma_f32_16x16x32_bf16 v[52:55], v[234:237], v[192:195], v[52:55]
	ds_read_b64_tr_b16 v[208:209], v178 offset:24576
	ds_read_b64_tr_b16 v[210:211], v178 offset:28672
	v_exp_f32_e32 v75, v75
	s_waitcnt lgkmcnt(8)
	v_mfma_f32_16x16x32_bf16 v[24:27], v[238:241], v[184:187], v[24:27]
	v_exp_f32_e32 v76, v76
	v_mfma_f32_16x16x32_bf16 v[56:59], v[238:241], v[192:195], v[56:59]
	ds_read_b64_tr_b16 v[212:213], v179 offset:24576
	ds_read_b64_tr_b16 v[214:215], v179 offset:28672
	v_exp_f32_e32 v77, v77
	s_waitcnt lgkmcnt(8)
	v_mfma_f32_16x16x32_bf16 v[28:31], v[242:245], v[184:187], v[28:31]
	v_exp_f32_e32 v78, v78
	v_mfma_f32_16x16x32_bf16 v[60:63], v[242:245], v[192:195], v[60:63]
	ds_read_b64_tr_b16 v[230:231], v180 offset:24576
	ds_read_b64_tr_b16 v[232:233], v180 offset:28672
	v_exp_f32_e32 v79, v79
	s_waitcnt lgkmcnt(8)
	v_mfma_f32_16x16x32_bf16 v[0:3], v[200:203], v[188:191], v[0:3]
	v_exp_f32_e32 v80, v80
	v_mfma_f32_16x16x32_bf16 v[32:35], v[200:203], v[196:199], v[32:35]
	ds_read_b64_tr_b16 v[234:235], v182 offset:24576
	ds_read_b64_tr_b16 v[236:237], v182 offset:28672
	ds_read_b128 v[200:203], v172 offset:49152
	v_exp_f32_e32 v81, v81
	s_waitcnt lgkmcnt(9)
	v_mfma_f32_16x16x32_bf16 v[4:7], v[204:207], v[188:191], v[4:7]
	v_exp_f32_e32 v82, v82
	v_mfma_f32_16x16x32_bf16 v[36:39], v[204:207], v[196:199], v[36:39]
	ds_read_b64_tr_b16 v[238:239], v216 offset:24576
	ds_read_b64_tr_b16 v[240:241], v216 offset:28672
	ds_read_b128 v[204:207], v172 offset:53248
	v_exp_f32_e32 v83, v83
	s_waitcnt lgkmcnt(10)
	v_mfma_f32_16x16x32_bf16 v[8:11], v[208:211], v[188:191], v[8:11]
	v_exp_f32_e32 v84, v84
	v_mfma_f32_16x16x32_bf16 v[40:43], v[208:211], v[196:199], v[40:43]
	ds_read_b64_tr_b16 v[242:243], v217 offset:24576
	ds_read_b64_tr_b16 v[244:245], v217 offset:28672
	ds_read_b128 v[208:211], v172 offset:57344
	v_exp_f32_e32 v85, v85
	s_waitcnt lgkmcnt(11)
	v_mfma_f32_16x16x32_bf16 v[12:15], v[212:215], v[188:191], v[12:15]
	v_exp_f32_e32 v86, v86
	v_mfma_f32_16x16x32_bf16 v[44:47], v[212:215], v[196:199], v[44:47]
	ds_read_b128 v[212:215], v172 offset:61440
	v_exp_f32_e32 v87, v87
	s_waitcnt lgkmcnt(10)
	v_mfma_f32_16x16x32_bf16 v[16:19], v[230:233], v[188:191], v[16:19]
	v_exp_f32_e32 v88, v88
	v_mfma_f32_16x16x32_bf16 v[48:51], v[230:233], v[196:199], v[48:51]
	ds_read_b128 v[230:233], v173 offset:49152
	v_exp_f32_e32 v89, v89
	s_waitcnt lgkmcnt(9)
	v_mfma_f32_16x16x32_bf16 v[20:23], v[234:237], v[188:191], v[20:23]
	v_exp_f32_e32 v90, v90
	v_mfma_f32_16x16x32_bf16 v[52:55], v[234:237], v[196:199], v[52:55]
	ds_read_b128 v[234:237], v173 offset:53248
	v_exp_f32_e32 v91, v91
	s_waitcnt lgkmcnt(7)
	v_mfma_f32_16x16x32_bf16 v[24:27], v[238:241], v[188:191], v[24:27]
	v_exp_f32_e32 v92, v92
	v_mfma_f32_16x16x32_bf16 v[56:59], v[238:241], v[196:199], v[56:59]
	ds_read_b128 v[238:241], v173 offset:57344
	v_exp_f32_e32 v93, v93
	s_waitcnt lgkmcnt(5)
	v_mfma_f32_16x16x32_bf16 v[28:31], v[242:245], v[188:191], v[28:31]
	v_exp_f32_e32 v94, v94
	v_mfma_f32_16x16x32_bf16 v[60:63], v[242:245], v[196:199], v[60:63]
	ds_read_b128 v[242:245], v173 offset:61440
	v_exp_f32_e32 v95, v95
	s_waitcnt vmcnt(2)
	s_barrier
	v_mfma_f32_16x16x32_bf16 v[128:131], v[200:203], v[96:99], 0
	v_add_f32_e32 v169, v169, v64
	v_mfma_f32_16x16x32_bf16 v[132:135], v[200:203], v[112:115], 0
	ds_read_b128 v[200:203], v174 offset:49152
	v_add_f32_e32 v169, v169, v65
	v_cvt_pk_bf16_f32 v184, v64, v65
	v_mfma_f32_16x16x32_bf16 v[136:139], v[204:207], v[96:99], 0
	v_add_f32_e32 v169, v169, v66
	v_mfma_f32_16x16x32_bf16 v[140:143], v[204:207], v[112:115], 0
	ds_read_b128 v[204:207], v174 offset:53248
	v_add_f32_e32 v169, v169, v67
	v_cvt_pk_bf16_f32 v185, v66, v67
	s_waitcnt lgkmcnt(7)
	v_mfma_f32_16x16x32_bf16 v[144:147], v[208:211], v[96:99], 0
	v_add_f32_e32 v222, v222, v68
	v_mfma_f32_16x16x32_bf16 v[148:151], v[208:211], v[112:115], 0
	ds_read_b128 v[208:211], v174 offset:57344
	v_add_f32_e32 v222, v222, v69
	v_cvt_pk_bf16_f32 v186, v72, v73
	s_waitcnt lgkmcnt(7)
	v_mfma_f32_16x16x32_bf16 v[152:155], v[212:215], v[96:99], 0
	v_add_f32_e32 v222, v222, v70
	v_mfma_f32_16x16x32_bf16 v[156:159], v[212:215], v[112:115], 0
	ds_read_b128 v[212:215], v174 offset:61440
	v_add_f32_e32 v222, v222, v71
	v_cvt_pk_bf16_f32 v187, v74, v75
	s_waitcnt lgkmcnt(7)
	v_mfma_f32_16x16x32_bf16 v[128:131], v[230:233], v[100:103], v[128:131]
	v_add_f32_e32 v169, v169, v72
	v_mfma_f32_16x16x32_bf16 v[132:135], v[230:233], v[116:119], v[132:135]
	ds_read_b128 v[230:233], v175 offset:49152
	v_add_f32_e32 v169, v169, v73
	v_cvt_pk_bf16_f32 v188, v80, v81
	s_waitcnt lgkmcnt(7)
; #define SBAR() __builtin_amdgcn_sched_barrier(0)
; __device__ __forceinline__ void finishSM(f32x16& p0, f32x16& p1, float alpha, float& l_reg, bf16x8& pa0, bf16x8& pa1, bf16x8& pa2, bf16x8& pa3) {
;     ...
;   float ps = 0;
; #pragma unroll
;   for (int r = 0; r < 16; ++r) ps += p0[r];
; #pragma unroll
;   for (int r = 0; r < 16; ++r) ps += p1[r];
;   { auto rr = __builtin_amdgcn_permlane32_swap(__float_as_uint(ps), __float_as_uint(ps), false, false);
;     ps = __uint_as_float(rr[0]) + __uint_as_float(rr[1]); }
;   l_reg = l_reg * alpha + ps;
;     ...
;   PK4(p0, 0, pa0); PK4(p0, 8, pa1); PK4(p1, 0, pa2); PK4(p1, 8, pa3);
;     ...
; }
; __device__ __forceinline__ void qkt(f32x16& p0, f32x16& p1, const bf16* Ks, const bf16x8* qr, int r32, int hi) {
;   p0 = f32x16{}; p1 = f32x16{};
; #pragma unroll
;   for (int d0 = 0; d0 < 8; ++d0) { int cb = (d0 * 16 + hi * 8) * 2;
;     bf16x8 b0 = *reinterpret_cast<const bf16x8*>((const char*)Ks + KSWZ(r32, cb));
;     bf16x8 b1 = *reinterpret_cast<const bf16x8*>((const char*)Ks + KSWZ(32 + r32, cb));
;     p0 = __builtin_amdgcn_mfma_f32_32x32x16_bf16(b0, qr[d0], p0, 0, 0, 0);
;     p1 = __builtin_amdgcn_mfma_f32_32x32x16_bf16(b1, qr[d0], p1, 0, 0, 0); }
; }
; template <int D0> __device__ __forceinline__ void pv_one(f32x16& od, int vb, bf16x8 pa0, bf16x8 pa1, bf16x8 pa2, bf16x8 pa3) {
;   const s16x4 l0 = tr_read<v_rd_off(D0, 0, 0)>(vb), h0 = tr_read<v_rd_off(D0, 0, 1)>(vb), l1 = tr_read<v_rd_off(D0, 1, 0)>(vb), h1 = tr_read<v_rd_off(D0, 1, 1)>(vb);
;   const s16x4 l2 = tr_read<v_rd_off(D0, 2, 0)>(vb), h2 = tr_read<v_rd_off(D0, 2, 1)>(vb), l3 = tr_read<v_rd_off(D0, 3, 0)>(vb), h3 = tr_read<v_rd_off(D0, 3, 1)>(vb);
;   asm volatile("s_waitcnt lgkmcnt(0)" ::: "memory"); SBAR();
;     ...
;   od = __builtin_amdgcn_mfma_f32_32x32x16_bf16(pa0, PK(l0, h0), od, 0, 0, 0);
;   od = __builtin_amdgcn_mfma_f32_32x32x16_bf16(pa1, PK(l1, h1), od, 0, 0, 0);
;   od = __builtin_amdgcn_mfma_f32_32x32x16_bf16(pa2, PK(l2, h2), od, 0, 0, 0);
;   od = __builtin_amdgcn_mfma_f32_32x32x16_bf16(pa3, PK(l3, h3), od, 0, 0, 0);
;     ...
; }
; __device__ __forceinline__ void pv_d0(f32x16* o, int vb, bf16x8 pa0, bf16x8 pa1, bf16x8 pa2, bf16x8 pa3) {
;   pv_one<0>(o[0], vb, pa0, pa1, pa2, pa3); pv_one<1>(o[1], vb, pa0, pa1, pa2, pa3); pv_one<2>(o[2], vb, pa0, pa1, pa2, pa3); pv_one<3>(o[3], vb, pa0, pa1, pa2, pa3);
	v_mfma_f32_16x16x32_bf16 v[136:139], v[234:237], v[100:103], v[136:139]
	v_add_f32_e32 v169, v169, v74
	v_mfma_f32_16x16x32_bf16 v[140:143], v[234:237], v[116:119], v[140:143]
	ds_read_b128 v[234:237], v175 offset:53248
	v_add_f32_e32 v169, v169, v75
	v_cvt_pk_bf16_f32 v189, v82, v83
	s_waitcnt lgkmcnt(7)
	v_mfma_f32_16x16x32_bf16 v[144:147], v[238:241], v[100:103], v[144:147]
	v_add_f32_e32 v222, v222, v76
	v_mfma_f32_16x16x32_bf16 v[148:151], v[238:241], v[116:119], v[148:151]
	ds_read_b128 v[238:241], v175 offset:57344
	v_add_f32_e32 v222, v222, v77
	v_cvt_pk_bf16_f32 v190, v88, v89
	s_waitcnt lgkmcnt(7)
	v_mfma_f32_16x16x32_bf16 v[152:155], v[242:245], v[100:103], v[152:155]
	v_add_f32_e32 v222, v222, v78
	v_mfma_f32_16x16x32_bf16 v[156:159], v[242:245], v[116:119], v[156:159]
	ds_read_b128 v[242:245], v175 offset:61440
	v_add_f32_e32 v222, v222, v79
	v_cvt_pk_bf16_f32 v191, v90, v91
	s_waitcnt lgkmcnt(7)
	v_mfma_f32_16x16x32_bf16 v[128:131], v[200:203], v[104:107], v[128:131]
	v_add_f32_e32 v169, v169, v80
	v_mfma_f32_16x16x32_bf16 v[132:135], v[200:203], v[120:123], v[132:135]
	v_add_f32_e32 v169, v169, v81
	v_cvt_pk_bf16_f32 v192, v68, v69
	s_waitcnt lgkmcnt(6)
	v_mfma_f32_16x16x32_bf16 v[136:139], v[204:207], v[104:107], v[136:139]
	v_add_f32_e32 v169, v169, v82
	v_mfma_f32_16x16x32_bf16 v[140:143], v[204:207], v[120:123], v[140:143]
	v_add_f32_e32 v169, v169, v83
	v_cvt_pk_bf16_f32 v193, v70, v71
	s_waitcnt lgkmcnt(5)
	v_mfma_f32_16x16x32_bf16 v[144:147], v[208:211], v[104:107], v[144:147]
	v_add_f32_e32 v222, v222, v84
	v_mfma_f32_16x16x32_bf16 v[148:151], v[208:211], v[120:123], v[148:151]
	v_add_f32_e32 v222, v222, v85
	v_cvt_pk_bf16_f32 v194, v76, v77
	s_waitcnt lgkmcnt(4)
	v_mfma_f32_16x16x32_bf16 v[152:155], v[212:215], v[104:107], v[152:155]
	ds_read_b64_tr_b16 v[200:201], v176 offset:32768
	ds_read_b64_tr_b16 v[202:203], v176 offset:36864
	v_add_f32_e32 v222, v222, v86
	v_mfma_f32_16x16x32_bf16 v[156:159], v[212:215], v[120:123], v[156:159]
	v_add_f32_e32 v222, v222, v87
	v_cvt_pk_bf16_f32 v195, v78, v79
	s_waitcnt lgkmcnt(5)
	v_mfma_f32_16x16x32_bf16 v[128:131], v[230:233], v[108:111], v[128:131]
	ds_read_b64_tr_b16 v[204:205], v177 offset:32768
	ds_read_b64_tr_b16 v[206:207], v177 offset:36864
	v_add_f32_e32 v169, v169, v88
	v_mfma_f32_16x16x32_bf16 v[132:135], v[230:233], v[124:127], v[132:135]
	v_add_f32_e32 v169, v169, v89
	v_cvt_pk_bf16_f32 v196, v84, v85
	s_waitcnt lgkmcnt(6)
	v_mfma_f32_16x16x32_bf16 v[136:139], v[234:237], v[108:111], v[136:139]
	ds_read_b64_tr_b16 v[208:209], v178 offset:32768
	ds_read_b64_tr_b16 v[210:211], v178 offset:36864
	v_add_f32_e32 v169, v169, v90
	v_mfma_f32_16x16x32_bf16 v[140:143], v[234:237], v[124:127], v[140:143]
	v_add_f32_e32 v169, v169, v91
	v_cvt_pk_bf16_f32 v197, v86, v87
	s_waitcnt lgkmcnt(7)
	v_mfma_f32_16x16x32_bf16 v[144:147], v[238:241], v[108:111], v[144:147]
	ds_read_b64_tr_b16 v[212:213], v179 offset:32768
	ds_read_b64_tr_b16 v[214:215], v179 offset:36864
	v_add_f32_e32 v222, v222, v92
	v_mfma_f32_16x16x32_bf16 v[148:151], v[238:241], v[124:127], v[148:151]
	v_add_f32_e32 v222, v222, v93
	v_cvt_pk_bf16_f32 v198, v92, v93
	s_waitcnt lgkmcnt(8)
	v_mfma_f32_16x16x32_bf16 v[152:155], v[242:245], v[108:111], v[152:155]
	ds_read_b64_tr_b16 v[230:231], v180 offset:32768
	ds_read_b64_tr_b16 v[232:233], v180 offset:36864
	v_add_f32_e32 v222, v222, v94
	v_mfma_f32_16x16x32_bf16 v[156:159], v[242:245], v[124:127], v[156:159]
	v_add_f32_e32 v222, v222, v95
	v_cvt_pk_bf16_f32 v199, v94, v95
	s_waitcnt lgkmcnt(8)
	v_mfma_f32_16x16x32_bf16 v[0:3], v[200:203], v[184:187], v[0:3]
	v_exp_f32_e32 v128, v128
	v_mfma_f32_16x16x32_bf16 v[32:35], v[200:203], v[192:195], v[32:35]
	ds_read_b64_tr_b16 v[234:235], v182 offset:32768
	ds_read_b64_tr_b16 v[236:237], v182 offset:36864
	v_exp_f32_e32 v129, v129
	s_waitcnt lgkmcnt(8)
	v_mfma_f32_16x16x32_bf16 v[4:7], v[204:207], v[184:187], v[4:7]
	v_exp_f32_e32 v130, v130
	v_mfma_f32_16x16x32_bf16 v[36:39], v[204:207], v[192:195], v[36:39]
	ds_read_b64_tr_b16 v[238:239], v216 offset:32768
	ds_read_b64_tr_b16 v[240:241], v216 offset:36864
	v_exp_f32_e32 v131, v131
	s_waitcnt lgkmcnt(8)
	v_mfma_f32_16x16x32_bf16 v[8:11], v[208:211], v[184:187], v[8:11]
	v_exp_f32_e32 v132, v132
	v_mfma_f32_16x16x32_bf16 v[40:43], v[208:211], v[192:195], v[40:43]
	ds_read_b64_tr_b16 v[242:243], v217 offset:32768
	ds_read_b64_tr_b16 v[244:245], v217 offset:36864
	v_exp_f32_e32 v133, v133
	s_waitcnt lgkmcnt(8)
	v_mfma_f32_16x16x32_bf16 v[12:15], v[212:215], v[184:187], v[12:15]
	v_exp_f32_e32 v134, v134
	v_mfma_f32_16x16x32_bf16 v[44:47], v[212:215], v[192:195], v[44:47]
	ds_read_b64_tr_b16 v[200:201], v176 offset:40960
	ds_read_b64_tr_b16 v[202:203], v176 offset:45056
	v_exp_f32_e32 v135, v135
	s_waitcnt lgkmcnt(8)
	v_mfma_f32_16x16x32_bf16 v[16:19], v[230:233], v[184:187], v[16:19]
	v_exp_f32_e32 v136, v136
	v_mfma_f32_16x16x32_bf16 v[48:51], v[230:233], v[192:195], v[48:51]
	ds_read_b64_tr_b16 v[204:205], v177 offset:40960
	ds_read_b64_tr_b16 v[206:207], v177 offset:45056
	v_exp_f32_e32 v137, v137
	s_waitcnt lgkmcnt(8)
	v_mfma_f32_16x16x32_bf16 v[20:23], v[234:237], v[184:187], v[20:23]
	v_exp_f32_e32 v138, v138
	v_mfma_f32_16x16x32_bf16 v[52:55], v[234:237], v[192:195], v[52:55]
	ds_read_b64_tr_b16 v[208:209], v178 offset:40960
	ds_read_b64_tr_b16 v[210:211], v178 offset:45056
	v_exp_f32_e32 v139, v139
	s_waitcnt lgkmcnt(8)
	v_mfma_f32_16x16x32_bf16 v[24:27], v[238:241], v[184:187], v[24:27]
	v_exp_f32_e32 v140, v140
	v_mfma_f32_16x16x32_bf16 v[56:59], v[238:241], v[192:195], v[56:59]
	ds_read_b64_tr_b16 v[212:213], v179 offset:40960
	ds_read_b64_tr_b16 v[214:215], v179 offset:45056
	v_exp_f32_e32 v141, v141
	s_waitcnt lgkmcnt(8)
; __device__ __forceinline__ void partialSM(f32x16& p0, f32x16& p1, float& m_reg, float& mn, float& alpha) {
;     ...
;   for (int r = 0; r < 16; ++r) p0[r] = __builtin_amdgcn_exp2f(p0[r]);
; }
; __device__ __forceinline__ void finishSM(f32x16& p0, f32x16& p1, float alpha, float& l_reg, bf16x8& pa0, bf16x8& pa1, bf16x8& pa2, bf16x8& pa3) {
; #pragma unroll
;   for (int r = 0; r < 16; ++r) p1[r] = __builtin_amdgcn_exp2f(p1[r]);
;   float ps = 0;
; #pragma unroll
;   for (int r = 0; r < 16; ++r) ps += p0[r];
; #pragma unroll
;   for (int r = 0; r < 16; ++r) ps += p1[r];
;   { auto rr = __builtin_amdgcn_permlane32_swap(__float_as_uint(ps), __float_as_uint(ps), false, false);
;     ps = __uint_as_float(rr[0]) + __uint_as_float(rr[1]); }
;   l_reg = l_reg * alpha + ps;
;     ...
;   PK4(p0, 0, pa0); PK4(p0, 8, pa1); PK4(p1, 0, pa2); PK4(p1, 8, pa3);
;     ...
; }
; __device__ __forceinline__ void qkt(f32x16& p0, f32x16& p1, const bf16* Ks, const bf16x8* qr, int r32, int hi) {
;   p0 = f32x16{}; p1 = f32x16{};
; #pragma unroll
;   for (int d0 = 0; d0 < 8; ++d0) { int cb = (d0 * 16 + hi * 8) * 2;
;     bf16x8 b0 = *reinterpret_cast<const bf16x8*>((const char*)Ks + KSWZ(r32, cb));
;     bf16x8 b1 = *reinterpret_cast<const bf16x8*>((const char*)Ks + KSWZ(32 + r32, cb));
;     p0 = __builtin_amdgcn_mfma_f32_32x32x16_bf16(b0, qr[d0], p0, 0, 0, 0);
;     p1 = __builtin_amdgcn_mfma_f32_32x32x16_bf16(b1, qr[d0], p1, 0, 0, 0); }
; }
; __device__ __forceinline__ int v_st(int k, int c) { const int kk = (k & ~0xC) | ((k & 4) << 1) | ((k & 8) >> 1); return ((kk >> 3) * 4 + (c >> 5)) * 512 + ((kk & 7) * 32 + (c & 31)) * 2; }
; __device__ __forceinline__ int v_rd_base(int lane) { return ((lane & 3) << 3) | (((lane >> 2) & 3) << 6) | (((lane >> 4) & 1) << 5) | (((lane >> 5) & 1) << 8); }
; template <int OFF> __device__ __forceinline__ s16x4 tr_read(int vb) {
;   s16x4 r; asm volatile("ds_read_b64_tr_b16 %0, %1 offset:%2" : "=&v"(r) : "v"(vb), "i"(OFF) : "memory"); return r;
; }
; template <int D0> __device__ __forceinline__ void pv_one(f32x16& od, int vb, bf16x8 pa0, bf16x8 pa1, bf16x8 pa2, bf16x8 pa3) {
;   const s16x4 l0 = tr_read<v_rd_off(D0, 0, 0)>(vb), h0 = tr_read<v_rd_off(D0, 0, 1)>(vb), l1 = tr_read<v_rd_off(D0, 1, 0)>(vb), h1 = tr_read<v_rd_off(D0, 1, 1)>(vb);
	v_mfma_f32_16x16x32_bf16 v[28:31], v[242:245], v[184:187], v[28:31]
	v_exp_f32_e32 v142, v142
	v_mfma_f32_16x16x32_bf16 v[60:63], v[242:245], v[192:195], v[60:63]
	ds_read_b64_tr_b16 v[230:231], v180 offset:40960
	ds_read_b64_tr_b16 v[232:233], v180 offset:45056
	v_exp_f32_e32 v143, v143
	s_waitcnt lgkmcnt(8)
	v_mfma_f32_16x16x32_bf16 v[0:3], v[200:203], v[188:191], v[0:3]
	v_exp_f32_e32 v144, v144
	v_mfma_f32_16x16x32_bf16 v[32:35], v[200:203], v[196:199], v[32:35]
	ds_read_b64_tr_b16 v[234:235], v182 offset:40960
	ds_read_b64_tr_b16 v[236:237], v182 offset:45056
	v_exp_f32_e32 v145, v145
	s_waitcnt lgkmcnt(8)
	v_mfma_f32_16x16x32_bf16 v[4:7], v[204:207], v[188:191], v[4:7]
	v_exp_f32_e32 v146, v146
	v_mfma_f32_16x16x32_bf16 v[36:39], v[204:207], v[196:199], v[36:39]
	ds_read_b64_tr_b16 v[238:239], v216 offset:40960
	ds_read_b64_tr_b16 v[240:241], v216 offset:45056
	v_exp_f32_e32 v147, v147
	s_waitcnt lgkmcnt(8)
	v_mfma_f32_16x16x32_bf16 v[8:11], v[208:211], v[188:191], v[8:11]
	v_exp_f32_e32 v148, v148
	v_mfma_f32_16x16x32_bf16 v[40:43], v[208:211], v[196:199], v[40:43]
	ds_read_b64_tr_b16 v[242:243], v217 offset:40960
	ds_read_b64_tr_b16 v[244:245], v217 offset:45056
	v_exp_f32_e32 v149, v149
	s_waitcnt lgkmcnt(8)
	v_mfma_f32_16x16x32_bf16 v[12:15], v[212:215], v[188:191], v[12:15]
	v_exp_f32_e32 v150, v150
	v_mfma_f32_16x16x32_bf16 v[44:47], v[212:215], v[196:199], v[44:47]
	v_exp_f32_e32 v151, v151
	s_waitcnt lgkmcnt(6)
	v_mfma_f32_16x16x32_bf16 v[16:19], v[230:233], v[188:191], v[16:19]
	v_exp_f32_e32 v152, v152
	v_mfma_f32_16x16x32_bf16 v[48:51], v[230:233], v[196:199], v[48:51]
	v_exp_f32_e32 v153, v153
	s_waitcnt lgkmcnt(4)
	v_mfma_f32_16x16x32_bf16 v[20:23], v[234:237], v[188:191], v[20:23]
	v_exp_f32_e32 v154, v154
	v_mfma_f32_16x16x32_bf16 v[52:55], v[234:237], v[196:199], v[52:55]
	v_exp_f32_e32 v155, v155
	s_waitcnt lgkmcnt(2)
	v_mfma_f32_16x16x32_bf16 v[24:27], v[238:241], v[188:191], v[24:27]
	v_exp_f32_e32 v156, v156
	v_mfma_f32_16x16x32_bf16 v[56:59], v[238:241], v[196:199], v[56:59]
	v_exp_f32_e32 v157, v157
	s_waitcnt lgkmcnt(0)
	v_mfma_f32_16x16x32_bf16 v[28:31], v[242:245], v[188:191], v[28:31]
	v_exp_f32_e32 v158, v158
	v_mfma_f32_16x16x32_bf16 v[60:63], v[242:245], v[196:199], v[60:63]
	v_exp_f32_e32 v159, v159
	s_waitcnt lgkmcnt(0)
	s_waitcnt vmcnt(0)
	s_barrier
	v_add_f32_e32 v169, v169, v128
	v_add_f32_e32 v169, v169, v129
	v_cvt_pk_bf16_f32 v184, v128, v129
	v_add_f32_e32 v169, v169, v130
	v_add_f32_e32 v169, v169, v131
	v_cvt_pk_bf16_f32 v185, v130, v131
	v_add_f32_e32 v222, v222, v132
	v_add_f32_e32 v222, v222, v133
	v_cvt_pk_bf16_f32 v186, v136, v137
	v_add_f32_e32 v222, v222, v134
	v_add_f32_e32 v222, v222, v135
	v_cvt_pk_bf16_f32 v187, v138, v139
	v_add_f32_e32 v169, v169, v136
	v_add_f32_e32 v169, v169, v137
	v_cvt_pk_bf16_f32 v188, v144, v145
	v_add_f32_e32 v169, v169, v138
	v_add_f32_e32 v169, v169, v139
	v_cvt_pk_bf16_f32 v189, v146, v147
	v_add_f32_e32 v222, v222, v140
	v_add_f32_e32 v222, v222, v141
	v_cvt_pk_bf16_f32 v190, v152, v153
	v_add_f32_e32 v222, v222, v142
	v_add_f32_e32 v222, v222, v143
	v_cvt_pk_bf16_f32 v191, v154, v155
	v_add_f32_e32 v169, v169, v144
	v_add_f32_e32 v169, v169, v145
	v_cvt_pk_bf16_f32 v192, v132, v133
	v_add_f32_e32 v169, v169, v146
	v_add_f32_e32 v169, v169, v147
	v_cvt_pk_bf16_f32 v193, v134, v135
	v_add_f32_e32 v222, v222, v148
	v_add_f32_e32 v222, v222, v149
	v_cvt_pk_bf16_f32 v194, v140, v141
	ds_read_b64_tr_b16 v[200:201], v176 offset:49152
	ds_read_b64_tr_b16 v[202:203], v176 offset:53248
	v_add_f32_e32 v222, v222, v150
	v_add_f32_e32 v222, v222, v151
	v_cvt_pk_bf16_f32 v195, v142, v143
	ds_read_b64_tr_b16 v[204:205], v177 offset:49152
	ds_read_b64_tr_b16 v[206:207], v177 offset:53248
	v_add_f32_e32 v169, v169, v152
	v_add_f32_e32 v169, v169, v153
	v_cvt_pk_bf16_f32 v196, v148, v149
	ds_read_b64_tr_b16 v[208:209], v178 offset:49152
	ds_read_b64_tr_b16 v[210:211], v178 offset:53248
	v_add_f32_e32 v169, v169, v154
	v_add_f32_e32 v169, v169, v155
	v_cvt_pk_bf16_f32 v197, v150, v151
	ds_read_b64_tr_b16 v[212:213], v179 offset:49152
	ds_read_b64_tr_b16 v[214:215], v179 offset:53248
	v_add_f32_e32 v222, v222, v156
	v_add_f32_e32 v222, v222, v157
	v_cvt_pk_bf16_f32 v198, v156, v157
	ds_read_b64_tr_b16 v[230:231], v180 offset:49152
	ds_read_b64_tr_b16 v[232:233], v180 offset:53248
	v_add_f32_e32 v222, v222, v158
	v_add_f32_e32 v222, v222, v159
	v_cvt_pk_bf16_f32 v199, v158, v159
	s_waitcnt lgkmcnt(8)
	v_mfma_f32_16x16x32_bf16 v[0:3], v[200:203], v[184:187], v[0:3]
	v_mfma_f32_16x16x32_bf16 v[32:35], v[200:203], v[192:195], v[32:35]
	ds_read_b64_tr_b16 v[234:235], v182 offset:49152
	ds_read_b64_tr_b16 v[236:237], v182 offset:53248
	s_waitcnt lgkmcnt(8)
	v_mfma_f32_16x16x32_bf16 v[4:7], v[204:207], v[184:187], v[4:7]
	v_mfma_f32_16x16x32_bf16 v[36:39], v[204:207], v[192:195], v[36:39]
	ds_read_b64_tr_b16 v[238:239], v216 offset:49152
	ds_read_b64_tr_b16 v[240:241], v216 offset:53248
	s_waitcnt lgkmcnt(8)
	v_mfma_f32_16x16x32_bf16 v[8:11], v[208:211], v[184:187], v[8:11]
	v_mfma_f32_16x16x32_bf16 v[40:43], v[208:211], v[192:195], v[40:43]
	ds_read_b64_tr_b16 v[242:243], v217 offset:49152
	ds_read_b64_tr_b16 v[244:245], v217 offset:53248
	s_waitcnt lgkmcnt(8)
	v_mfma_f32_16x16x32_bf16 v[12:15], v[212:215], v[184:187], v[12:15]
	v_mfma_f32_16x16x32_bf16 v[44:47], v[212:215], v[192:195], v[44:47]
	ds_read_b64_tr_b16 v[200:201], v176 offset:57344
	ds_read_b64_tr_b16 v[202:203], v176 offset:61440
	s_waitcnt lgkmcnt(8)
	v_mfma_f32_16x16x32_bf16 v[16:19], v[230:233], v[184:187], v[16:19]
	v_mfma_f32_16x16x32_bf16 v[48:51], v[230:233], v[192:195], v[48:51]
	ds_read_b64_tr_b16 v[204:205], v177 offset:57344
	ds_read_b64_tr_b16 v[206:207], v177 offset:61440
	s_waitcnt lgkmcnt(8)
; #define SBAR() __builtin_amdgcn_sched_barrier(0)
; #define RESC(a) do { if (__any((a) < 1.f)) { if (hi == 0) al_l[r32] = (a); asm volatile("s_waitcnt lgkmcnt(0)" ::: "memory"); \
;     _Pragma("unroll") for (int d = 0; d < 4; ++d) _Pragma("unroll") for (int r = 0; r < 16; ++r) o[d][r] *= al_l[crow(r, hi)]; } } while (0)
; template <int D0> __device__ __forceinline__ void pv_one(f32x16& od, int vb, bf16x8 pa0, bf16x8 pa1, bf16x8 pa2, bf16x8 pa3) {
;   const s16x4 l0 = tr_read<v_rd_off(D0, 0, 0)>(vb), h0 = tr_read<v_rd_off(D0, 0, 1)>(vb), l1 = tr_read<v_rd_off(D0, 1, 0)>(vb), h1 = tr_read<v_rd_off(D0, 1, 1)>(vb);
;   const s16x4 l2 = tr_read<v_rd_off(D0, 2, 0)>(vb), h2 = tr_read<v_rd_off(D0, 2, 1)>(vb), l3 = tr_read<v_rd_off(D0, 3, 0)>(vb), h3 = tr_read<v_rd_off(D0, 3, 1)>(vb);
;   asm volatile("s_waitcnt lgkmcnt(0)" ::: "memory"); SBAR();
;     ...
;   od = __builtin_amdgcn_mfma_f32_32x32x16_bf16(pa0, PK(l0, h0), od, 0, 0, 0);
;   od = __builtin_amdgcn_mfma_f32_32x32x16_bf16(pa1, PK(l1, h1), od, 0, 0, 0);
;   od = __builtin_amdgcn_mfma_f32_32x32x16_bf16(pa2, PK(l2, h2), od, 0, 0, 0);
;   od = __builtin_amdgcn_mfma_f32_32x32x16_bf16(pa3, PK(l3, h3), od, 0, 0, 0);
;     ...
; }
; __device__ __forceinline__ void pv_d0(f32x16* o, int vb, bf16x8 pa0, bf16x8 pa1, bf16x8 pa2, bf16x8 pa3) {
;   pv_one<0>(o[0], vb, pa0, pa1, pa2, pa3); pv_one<1>(o[1], vb, pa0, pa1, pa2, pa3); pv_one<2>(o[2], vb, pa0, pa1, pa2, pa3); pv_one<3>(o[3], vb, pa0, pa1, pa2, pa3);
;     ...
;   { SBAR(); qkt(pB0, pB1, KSUB(1, 1), qr, r32, hi);
;     finishSM(pA0, pA1, alA, l_reg, pa0, pa1, pa2, pa3); SBAR();
;     pv_d0(o, VSUB(1, 0), pa0, pa1, pa2, pa3); partialSM(pB0, pB1, m_reg, mnB, alB);
;     RESC(alB);
;     finishSM(pB0, pB1, alB, l_reg, pa0, pa1, pa2, pa3); SBAR();
;     pv_d0(o, VSUB(1, 1), pa0, pa1, pa2, pa3); }
	v_mfma_f32_16x16x32_bf16 v[20:23], v[234:237], v[184:187], v[20:23]
	v_mfma_f32_16x16x32_bf16 v[52:55], v[234:237], v[192:195], v[52:55]
	ds_read_b64_tr_b16 v[208:209], v178 offset:57344
	ds_read_b64_tr_b16 v[210:211], v178 offset:61440
	s_waitcnt lgkmcnt(8)
	v_mfma_f32_16x16x32_bf16 v[24:27], v[238:241], v[184:187], v[24:27]
	v_mfma_f32_16x16x32_bf16 v[56:59], v[238:241], v[192:195], v[56:59]
	ds_read_b64_tr_b16 v[212:213], v179 offset:57344
	ds_read_b64_tr_b16 v[214:215], v179 offset:61440
	s_waitcnt lgkmcnt(8)
	v_mfma_f32_16x16x32_bf16 v[28:31], v[242:245], v[184:187], v[28:31]
	v_mfma_f32_16x16x32_bf16 v[60:63], v[242:245], v[192:195], v[60:63]
	ds_read_b64_tr_b16 v[230:231], v180 offset:57344
	ds_read_b64_tr_b16 v[232:233], v180 offset:61440
	s_waitcnt lgkmcnt(8)
	v_mfma_f32_16x16x32_bf16 v[0:3], v[200:203], v[188:191], v[0:3]
	v_mfma_f32_16x16x32_bf16 v[32:35], v[200:203], v[196:199], v[32:35]
	ds_read_b64_tr_b16 v[234:235], v182 offset:57344
	ds_read_b64_tr_b16 v[236:237], v182 offset:61440
	s_waitcnt lgkmcnt(8)
	v_mfma_f32_16x16x32_bf16 v[4:7], v[204:207], v[188:191], v[4:7]
	v_mfma_f32_16x16x32_bf16 v[36:39], v[204:207], v[196:199], v[36:39]
	ds_read_b64_tr_b16 v[238:239], v216 offset:57344
	ds_read_b64_tr_b16 v[240:241], v216 offset:61440
	s_waitcnt lgkmcnt(8)
	v_mfma_f32_16x16x32_bf16 v[8:11], v[208:211], v[188:191], v[8:11]
	v_mfma_f32_16x16x32_bf16 v[40:43], v[208:211], v[196:199], v[40:43]
	ds_read_b64_tr_b16 v[242:243], v217 offset:57344
	ds_read_b64_tr_b16 v[244:245], v217 offset:61440
	s_waitcnt lgkmcnt(8)
	v_mfma_f32_16x16x32_bf16 v[12:15], v[212:215], v[188:191], v[12:15]
	v_mfma_f32_16x16x32_bf16 v[44:47], v[212:215], v[196:199], v[44:47]
	s_waitcnt lgkmcnt(6)
	v_mfma_f32_16x16x32_bf16 v[16:19], v[230:233], v[188:191], v[16:19]
	v_mfma_f32_16x16x32_bf16 v[48:51], v[230:233], v[196:199], v[48:51]
	s_waitcnt lgkmcnt(4)
	v_mfma_f32_16x16x32_bf16 v[20:23], v[234:237], v[188:191], v[20:23]
	v_mfma_f32_16x16x32_bf16 v[52:55], v[234:237], v[196:199], v[52:55]
	s_waitcnt lgkmcnt(2)
	v_mfma_f32_16x16x32_bf16 v[24:27], v[238:241], v[188:191], v[24:27]
	v_mfma_f32_16x16x32_bf16 v[56:59], v[238:241], v[196:199], v[56:59]
	s_waitcnt lgkmcnt(0)
	v_mfma_f32_16x16x32_bf16 v[28:31], v[242:245], v[188:191], v[28:31]
	v_mfma_f32_16x16x32_bf16 v[60:63], v[242:245], v[196:199], v[60:63]
	s_waitcnt lgkmcnt(0)
	s_waitcnt vmcnt(0)
	s_barrier
; __device__ __forceinline__ int crow(int r, int hi) { return (r & 3) + 8 * (r >> 2) + 4 * hi; }
;     ...
;   if (hi == 0) li_l[r32] = l_reg; asm volatile("s_waitcnt lgkmcnt(0)" ::: "memory");
;   if constexpr (MODE == 1) { if (hi == 0) lse_out[(long)(wid * QBLK + r32) * lse_stride] = m_reg * SCALE + __logf(l_reg); }
;   float rli[16];
; #pragma unroll
;   for (int r = 0; r < 16; ++r) rli[r] = __builtin_amdgcn_rcpf(li_l[crow(r, hi)]);
;   bf16* Ow = Ob + (long)(wid * QBLK) * ldo;
; #pragma unroll
;   for (int r = 0; r < 16; ++r) { const int orow = crow(r, hi);
; #pragma unroll
;     for (int d0 = 0; d0 < 4; ++d0) Ow[(long)orow * ldo + d0 * 32 + r32] = __float2bfloat16(o[d0][r] * rli[r]); }
	s_setprio 0
	v_and_b32_e32 v64, 63, v218
	v_lshlrev_b32_e32 v64, 2, v64
	v_xor_b32_e32 v65, 64, v64
	v_xor_b32_e32 v66, 0x80, v64
	ds_bpermute_b32 v67, v65, v169
	s_waitcnt lgkmcnt(0)
	v_add_f32_e32 v169, v169, v67
	ds_bpermute_b32 v67, v66, v169
	s_waitcnt lgkmcnt(0)
	v_add_f32_e32 v169, v169, v67
	v_rcp_f32_e32 v169, v169
	ds_bpermute_b32 v67, v65, v222
	s_waitcnt lgkmcnt(0)
	v_add_f32_e32 v222, v222, v67
	ds_bpermute_b32 v67, v66, v222
	s_waitcnt lgkmcnt(0)
	v_add_f32_e32 v222, v222, v67
	v_rcp_f32_e32 v222, v222
	s_lshl_b64 s[0:1], s[20:21], 12
	s_add_u32 s0, s24, s0
	s_addc_u32 s1, s25, s1
	s_lshl_b32 s2, s14, 1
	s_add_u32 s2, s0, s2
	s_addc_u32 s3, s1, 0
	s_ashr_i32 s39, s38, 31
	s_lshl_b64 s[0:1], s[38:39], 12
	s_add_u32 s0, s2, s0
	s_addc_u32 s1, s3, s1
	v_and_b32_e32 v64, 63, v218
	v_and_b32_e32 v65, 15, v64
	v_lshrrev_b32_e32 v66, 4, v64
	v_lshlrev_b32_e32 v66, 3, v66
	v_lshl_or_b32 v68, v65, 12, v66
	v_add_u32_e32 v69, 0x10000, v68
	v_mul_f32_e32 v0, v0, v169
	v_mul_f32_e32 v1, v1, v169
	v_mul_f32_e32 v2, v2, v169
	v_mul_f32_e32 v3, v3, v169
	v_cvt_pk_bf16_f32 v130, v0, v1
	v_cvt_pk_bf16_f32 v131, v2, v3
	global_store_dwordx2 v68, v[130:131], s[0:1] offset:0
	v_mul_f32_e32 v4, v4, v169
	v_mul_f32_e32 v5, v5, v169
	v_mul_f32_e32 v6, v6, v169
	v_mul_f32_e32 v7, v7, v169
	v_cvt_pk_bf16_f32 v132, v4, v5
	v_cvt_pk_bf16_f32 v133, v6, v7
	global_store_dwordx2 v68, v[132:133], s[0:1] offset:32
	v_mul_f32_e32 v8, v8, v169
	v_mul_f32_e32 v9, v9, v169
	v_mul_f32_e32 v10, v10, v169
	v_mul_f32_e32 v11, v11, v169
	v_cvt_pk_bf16_f32 v134, v8, v9
	v_cvt_pk_bf16_f32 v135, v10, v11
	global_store_dwordx2 v68, v[134:135], s[0:1] offset:64
	v_mul_f32_e32 v12, v12, v169
	v_mul_f32_e32 v13, v13, v169
	v_mul_f32_e32 v14, v14, v169
	v_mul_f32_e32 v15, v15, v169
	v_cvt_pk_bf16_f32 v136, v12, v13
	v_cvt_pk_bf16_f32 v137, v14, v15
	global_store_dwordx2 v68, v[136:137], s[0:1] offset:96
	v_mul_f32_e32 v16, v16, v169
	v_mul_f32_e32 v17, v17, v169
	v_mul_f32_e32 v18, v18, v169
	v_mul_f32_e32 v19, v19, v169
	v_cvt_pk_bf16_f32 v138, v16, v17
	v_cvt_pk_bf16_f32 v139, v18, v19
	global_store_dwordx2 v68, v[138:139], s[0:1] offset:128
	v_mul_f32_e32 v20, v20, v169
	v_mul_f32_e32 v21, v21, v169
	v_mul_f32_e32 v22, v22, v169
	v_mul_f32_e32 v23, v23, v169
	v_cvt_pk_bf16_f32 v140, v20, v21
	v_cvt_pk_bf16_f32 v141, v22, v23
	global_store_dwordx2 v68, v[140:141], s[0:1] offset:160
	v_mul_f32_e32 v24, v24, v169
	v_mul_f32_e32 v25, v25, v169
	v_mul_f32_e32 v26, v26, v169
	v_mul_f32_e32 v27, v27, v169
	v_cvt_pk_bf16_f32 v142, v24, v25
	v_cvt_pk_bf16_f32 v143, v26, v27
	global_store_dwordx2 v68, v[142:143], s[0:1] offset:192
	v_mul_f32_e32 v28, v28, v169
	v_mul_f32_e32 v29, v29, v169
	v_mul_f32_e32 v30, v30, v169
	v_mul_f32_e32 v31, v31, v169
	v_cvt_pk_bf16_f32 v144, v28, v29
	v_cvt_pk_bf16_f32 v145, v30, v31
	global_store_dwordx2 v68, v[144:145], s[0:1] offset:224
	v_mul_f32_e32 v32, v32, v222
	v_mul_f32_e32 v33, v33, v222
	v_mul_f32_e32 v34, v34, v222
	v_mul_f32_e32 v35, v35, v222
	v_cvt_pk_bf16_f32 v130, v32, v33
	v_cvt_pk_bf16_f32 v131, v34, v35
	global_store_dwordx2 v69, v[130:131], s[0:1] offset:0
	v_mul_f32_e32 v36, v36, v222
	v_mul_f32_e32 v37, v37, v222
	v_mul_f32_e32 v38, v38, v222
	v_mul_f32_e32 v39, v39, v222
	v_cvt_pk_bf16_f32 v132, v36, v37
	v_cvt_pk_bf16_f32 v133, v38, v39
	global_store_dwordx2 v69, v[132:133], s[0:1] offset:32
	v_mul_f32_e32 v40, v40, v222
	v_mul_f32_e32 v41, v41, v222
	v_mul_f32_e32 v42, v42, v222
	v_mul_f32_e32 v43, v43, v222
	v_cvt_pk_bf16_f32 v134, v40, v41
	v_cvt_pk_bf16_f32 v135, v42, v43
	global_store_dwordx2 v69, v[134:135], s[0:1] offset:64
	v_mul_f32_e32 v44, v44, v222
	v_mul_f32_e32 v45, v45, v222
	v_mul_f32_e32 v46, v46, v222
	v_mul_f32_e32 v47, v47, v222
	v_cvt_pk_bf16_f32 v136, v44, v45
	v_cvt_pk_bf16_f32 v137, v46, v47
	global_store_dwordx2 v69, v[136:137], s[0:1] offset:96
	v_mul_f32_e32 v48, v48, v222
	v_mul_f32_e32 v49, v49, v222
	v_mul_f32_e32 v50, v50, v222
	v_mul_f32_e32 v51, v51, v222
	v_cvt_pk_bf16_f32 v138, v48, v49
	v_cvt_pk_bf16_f32 v139, v50, v51
	global_store_dwordx2 v69, v[138:139], s[0:1] offset:128
	v_mul_f32_e32 v52, v52, v222
	v_mul_f32_e32 v53, v53, v222
	v_mul_f32_e32 v54, v54, v222
	v_mul_f32_e32 v55, v55, v222
	v_cvt_pk_bf16_f32 v140, v52, v53
	v_cvt_pk_bf16_f32 v141, v54, v55
	global_store_dwordx2 v69, v[140:141], s[0:1] offset:160
	v_mul_f32_e32 v56, v56, v222
	v_mul_f32_e32 v57, v57, v222
	v_mul_f32_e32 v58, v58, v222
	v_mul_f32_e32 v59, v59, v222
	v_cvt_pk_bf16_f32 v142, v56, v57
	v_cvt_pk_bf16_f32 v143, v58, v59
	global_store_dwordx2 v69, v[142:143], s[0:1] offset:192
	v_mul_f32_e32 v60, v60, v222
	v_mul_f32_e32 v61, v61, v222
	v_mul_f32_e32 v62, v62, v222
	v_mul_f32_e32 v63, v63, v222
	v_cvt_pk_bf16_f32 v144, v60, v61
	v_cvt_pk_bf16_f32 v145, v62, v63
	global_store_dwordx2 v69, v[144:145], s[0:1] offset:224
	v_lshlrev_b32_e32 v164, 4, v229
	v_mov_b32_e32 v165, 0
	s_mov_b32 s50, -1
	s_barrier
	s_branch .LBB0_478
